# 16x16x32 GEMM loops: srcA operand rows permuted (bits 2,3 exchanged) so a single v_permlane16_swap per accumulator pair restores the 32x32 layout (32 instead of 64 fixup swaps per tile)
# baseline (speedup 1.0000x reference)
; template <bool SWAP, class Epi>
; DI void gemm_tile(const u16* __restrict__ A, int lda, const u16* __restrict__ Bt, int ldb, int K, int m0, int n0, char* smem, Epi&& epi) {
;     ...
;   const int tid = threadIdx.x, lane = tid & 63, w = tid >> 6, wm = w >> 1, wn = w & 1;
;   const int r = lane & 31, hi = lane >> 5;
;   f32x16 acc[2][2];
; #pragma unroll
;   for (int a = 0; a < 2; ++a)
; #pragma unroll
;     for (int b = 0; b < 2; ++b)
; #pragma unroll
;       for (int i = 0; i < 16; ++i) acc[a][b][i] = 0.f;
;   const int srow = tid >> 3, skc = tid & 7;
;   const u16* ag = A + (size_t)(m0 + srow) * lda + skc * 8;
;   const u16* bg = Bt + (size_t)(n0 + srow) * ldb + skc * 8;
;   u16* asw = As + srow * 72 + skc * 8;
;   u16* bsw = Bs + srow * 72 + skc * 8;
;   u32x4 ra0[4], rb0[4], ra1[4], rb1[4];
; #pragma unroll
;   for (int i = 0; i < 4; ++i) { ra0[i] = *(const u32x4*)(ag + (size_t)i * 32 * lda); rb0[i] = *(const u32x4*)(bg + (size_t)i * 32 * ldb); }
; #pragma unroll
;   for (int i = 0; i < 4; ++i) { ra1[i] = *(const u32x4*)(ag + (size_t)i * 32 * lda + 64); rb1[i] = *(const u32x4*)(bg + (size_t)i * 32 * ldb + 64); }
;   __syncthreads();
; #pragma unroll
;   for (int i = 0; i < 4; ++i) { *(u32x4*)(asw + 32 * i * 72) = ra0[i]; *(u32x4*)(bsw + 32 * i * 72) = rb0[i]; }
;   __syncthreads();
;   const int KT = K >> 6;
;   const u16* Asb = As + (wm * 64 + r) * 72 + hi * 8;
;   const u16* Bsb = Bs + (wn * 64 + r) * 72 + hi * 8;
; DI void phase2(const Params& p, char* smem, int rep) {
;     ...
;   for (int it = blockIdx.x; it < 64 * 32; it += gridDim.x) {
;     const int tn = it / 64, tm = it % 64;
;     gemm_tile<true>(H, D_, W, D_, D_, tm * 128, tn * 128, smem, [&](f32x16 (&acc)[2][2], int mb, int nb, int r, int hi) __attribute__((always_inline)) {
.Lprio_p2:
	s_cmpk_gt_i32 s12, 0x7ff
	s_cbranch_scc1 .LBB0_398
	v_lshlrev_b32_e32 v2, 4, v0
	v_and_b32_e32 v130, 0x70, v2
	v_mov_b32_e32 v131, 0
	v_lshl_add_u64 v[2:3], s[82:83], 0, v[130:131]
	s_mov_b64 s[2:3], 0x6538000
	v_lshrrev_b32_e32 v1, 3, v0
	v_lshl_add_u64 v[132:133], v[2:3], 0, s[2:3]
	s_mov_b64 s[2:3], 0xb8000
	v_lshl_add_u64 v[134:135], v[2:3], 0, s[2:3]
	v_mul_u32_u24_e32 v2, 0x48, v1
	v_and_b32_e32 v4, 31, v0
	v_lshlrev_b32_e32 v2, 1, v2
	v_lshrrev_b32_e32 v3, 1, v0
	v_add3_u32 v146, 0, v2, v130
	v_bfe_u32 v2, v0, 5, 1
	v_and_or_b32 v148, v3, 64, v4
	s_load_dword s13, s[0:1], 0xc0
	s_add_u32 s4, s82, 0x8538000
	v_mul_u32_u24_e32 v3, 0x90, v148
	v_lshlrev_b32_e32 v4, 4, v2
	s_addc_u32 s5, s83, 0
	v_add3_u32 v149, 0, v3, v4
	v_and_b32_e32 v3, 0x5f, v0
	v_lshlrev_b32_e32 v152, 2, v2
	v_cmp_eq_u32_e64 s[2:3], 0, v2
	v_and_b32_e32 v2, 7, v0
	s_add_u32 s6, s82, 0x18320000
	v_mul_u32_u24_e32 v3, 0x90, v3
	v_lshlrev_b32_e32 v136, 4, v2
	v_mbcnt_lo_u32_b32 v2, -1, 0
	s_addc_u32 s7, s83, 0
	v_add_u32_e32 v147, 0x9010, v146
	v_add3_u32 v150, 0, v3, v4
	v_and_b32_e32 v151, 64, v0
	v_mov_b32_e32 v137, v131
	s_mov_b32 s16, 0x20000
	s_mov_b32 s17, 0x40000
	s_mov_b32 s18, 0x60000
	s_mov_b64 s[8:9], 0x100
	s_movk_i32 s19, 0x2080
	s_movk_i32 s20, 0xbff
	v_mbcnt_hi_u32_b32 v153, -1, v2
	s_mov_b32 s21, s12
	v_lshrrev_b32_e32 v198, 3, v0
	v_lshrrev_b32_e32 v199, 2, v198
	v_lshrrev_b32_e32 v200, 3, v198
	v_xor_b32_e32 v199, v199, v200
	v_and_b32_e32 v199, 1, v199
	v_and_b32_e32 v200, 1, v0
	v_lshlrev_b32_e32 v200, 5, v200
	v_sub_u32_e32 v200, 16, v200
	v_mul_lo_u32 v199, v199, v200
	v_add_u32_e32 v146, v146, v199
	v_add_u32_e32 v147, v147, v199
	v_and_b32_e32 v198, 15, v0
	v_bfe_u32 v199, v0, 4, 2
	v_lshrrev_b32_e32 v200, 2, v198
	v_lshrrev_b32_e32 v201, 3, v198
	v_xor_b32_e32 v200, v200, v201
	v_and_b32_e32 v200, 1, v200
	v_xor_b32_e32 v199, v199, v200
	v_lshlrev_b32_e32 v199, 4, v199
	v_bfe_u32 v200, v0, 7, 1
	v_lshl_or_b32 v200, v200, 6, v198
	v_mul_u32_u24_e32 v200, 0x90, v200
	v_add_u32_e32 v149, v200, v199
	v_and_b32_e32 v201, 3, v198
	v_and_b32_e32 v202, 4, v198
	v_lshlrev_b32_e32 v202, 1, v202
	v_and_b32_e32 v203, 8, v198
	v_lshrrev_b32_e32 v203, 1, v203
	v_or3_b32 v198, v201, v202, v203
	v_bfe_u32 v200, v0, 6, 1
	v_lshl_or_b32 v200, v200, 6, v198
	v_mul_u32_u24_e32 v200, 0x90, v200
	v_add_u32_e32 v150, v200, v199
	s_branch .LBB0_385

; #define MFMA(a, b, c) __builtin_amdgcn_mfma_f32_32x32x16_bf16((a), (b), (c), 0, 0, 0)
; template <bool SWAP, class Epi>
; DI void gemm_tile(const u16* __restrict__ A, int lda, const u16* __restrict__ Bt, int ldb, int K, int m0, int n0, char* smem, Epi&& epi) {
;     ...
;   auto compute = [&](int buf) __attribute__((always_inline)) {
;     bf16x8 af[2][2], bfr[2][2];
;     af[0][0] = *(const bf16x8*)(Asb + buf * 128 * 72);
;     af[0][1] = *(const bf16x8*)(Asb + buf * 128 * 72 + 32 * 72);
;     bfr[0][0] = *(const bf16x8*)(Bsb + buf * 128 * 72);
;     bfr[0][1] = *(const bf16x8*)(Bsb + buf * 128 * 72 + 32 * 72);
; #pragma unroll
;     for (int ks = 0; ks < 4; ++ks) {
;       const int c = ks & 1, n = c ^ 1;
;       if (ks < 3) {
;         af[n][0] = *(const bf16x8*)(Asb + buf * 128 * 72 + (ks + 1) * 16);
;         af[n][1] = *(const bf16x8*)(Asb + buf * 128 * 72 + 32 * 72 + (ks + 1) * 16);
;         bfr[n][0] = *(const bf16x8*)(Bsb + buf * 128 * 72 + (ks + 1) * 16);
;         bfr[n][1] = *(const bf16x8*)(Bsb + buf * 128 * 72 + 32 * 72 + (ks + 1) * 16);
;       }
;       __builtin_amdgcn_sched_barrier(0);
; #pragma unroll
;       for (int mi = 0; mi < 2; ++mi)
; #pragma unroll
;         for (int ni = 0; ni < 2; ++ni) {
;           if (SWAP) acc[mi][ni] = MFMA(bfr[c][ni], af[c][mi], acc[mi][ni]);
;           else acc[mi][ni] = MFMA(af[c][mi], bfr[c][ni], acc[mi][ni]);
;         }
;       __builtin_amdgcn_sched_barrier(0);
;     }
;   };
;   for (int kt = 0; kt < KT; kt += 2) {
;     if (kt + 2 < KT) {
;       const int k0 = (kt + 2) << 6;
; #pragma unroll
;       for (int i = 0; i < 4; ++i) { ra0[i] = *(const u32x4*)(ag + (size_t)i * 32 * lda + k0); rb0[i] = *(const u32x4*)(bg + (size_t)i * 32 * ldb + k0); }
;     }
;     compute(0);
; #pragma unroll
;     for (int i = 0; i < 4; ++i) { *(u32x4*)(asw + 128 * 72 + 32 * i * 72) = ra1[i]; *(u32x4*)(bsw + 128 * 72 + 32 * i * 72) = rb1[i]; }
;     __syncthreads();
;     if (kt + 3 < KT) {
;       const int k0 = (kt + 3) << 6;
; #pragma unroll
;       for (int i = 0; i < 4; ++i) { ra1[i] = *(const u32x4*)(ag + (size_t)i * 32 * lda + k0); rb1[i] = *(const u32x4*)(bg + (size_t)i * 32 * ldb + k0); }
;     }
;     compute(1);
.LBB0_387:
	global_load_dwordx4 v[66:69], v194, s[100:101] offset:256
	global_load_dwordx4 v[70:73], v190, s[98:99] offset:256
	global_load_dwordx4 v[74:77], v195, s[100:101] offset:256
	global_load_dwordx4 v[78:81], v191, s[98:99] offset:256
	global_load_dwordx4 v[82:85], v196, s[100:101] offset:256
	global_load_dwordx4 v[86:89], v192, s[98:99] offset:256
	global_load_dwordx4 v[90:93], v197, s[100:101] offset:256
	global_load_dwordx4 v[94:97], v193, s[98:99] offset:256
	ds_read_b128 v[170:173], v150 offset:36880
	ds_read_b128 v[154:157], v149 offset:16
	ds_read_b128 v[158:161], v149 offset:2320
	ds_read_b128 v[174:177], v150 offset:39184
	ds_read_b128 v[162:165], v149 offset:4624
	ds_read_b128 v[166:169], v149 offset:6928
	ds_read_b128 v[178:181], v150 offset:41488
	ds_read_b128 v[182:185], v150 offset:43792
	s_waitcnt lgkmcnt(6)
	v_mfma_f32_16x16x32_bf16 v[50:53], v[170:173], v[154:157], v[50:53]
	s_waitcnt lgkmcnt(5)
	v_mfma_f32_16x16x32_bf16 v[54:57], v[170:173], v[158:161], v[54:57]
	s_waitcnt lgkmcnt(4)
	v_mfma_f32_16x16x32_bf16 v[58:61], v[174:177], v[154:157], v[58:61]
	v_mfma_f32_16x16x32_bf16 v[62:65], v[174:177], v[158:161], v[62:65]
	ds_read_b128 v[214:217], v150 offset:36944
	ds_read_b128 v[198:201], v149 offset:80
	ds_read_b128 v[202:205], v149 offset:2384
	ds_read_b128 v[218:221], v150 offset:39248
	s_waitcnt lgkmcnt(7)
	v_mfma_f32_16x16x32_bf16 v[18:21], v[170:173], v[162:165], v[18:21]
	v_mfma_f32_16x16x32_bf16 v[26:29], v[174:177], v[162:165], v[26:29]
	s_waitcnt lgkmcnt(6)
	v_mfma_f32_16x16x32_bf16 v[22:25], v[170:173], v[166:169], v[22:25]
	v_mfma_f32_16x16x32_bf16 v[30:33], v[174:177], v[166:169], v[30:33]
	ds_read_b128 v[206:209], v149 offset:4688
	ds_read_b128 v[210:213], v149 offset:6992
	ds_read_b128 v[222:225], v150 offset:41552
	ds_read_b128 v[226:229], v150 offset:43856
	s_waitcnt lgkmcnt(9)
	v_mfma_f32_16x16x32_bf16 v[34:37], v[178:181], v[154:157], v[34:37]
	v_mfma_f32_16x16x32_bf16 v[38:41], v[178:181], v[158:161], v[38:41]
	v_mfma_f32_16x16x32_bf16 v[2:5], v[178:181], v[162:165], v[2:5]
	v_mfma_f32_16x16x32_bf16 v[6:9], v[178:181], v[166:169], v[6:9]
	s_waitcnt lgkmcnt(8)
	v_mfma_f32_16x16x32_bf16 v[42:45], v[182:185], v[154:157], v[42:45]
	v_mfma_f32_16x16x32_bf16 v[46:49], v[182:185], v[158:161], v[46:49]
	s_waitcnt vmcnt(14)
	ds_write_b128 v146, v[98:101] offset:18448
	ds_write_b128 v146, v[102:105] offset:55312
	v_mfma_f32_16x16x32_bf16 v[10:13], v[182:185], v[162:165], v[10:13]
	v_mfma_f32_16x16x32_bf16 v[14:17], v[182:185], v[166:169], v[14:17]
	s_waitcnt lgkmcnt(8)
	v_mfma_f32_16x16x32_bf16 v[50:53], v[214:217], v[198:201], v[50:53]
	s_waitcnt lgkmcnt(7)
	v_mfma_f32_16x16x32_bf16 v[54:57], v[214:217], v[202:205], v[54:57]
	s_waitcnt vmcnt(12)
	ds_write_b128 v146, v[106:109] offset:23056
	ds_write_b128 v146, v[110:113] offset:59920
	s_waitcnt lgkmcnt(8)
	v_mfma_f32_16x16x32_bf16 v[58:61], v[218:221], v[198:201], v[58:61]
	v_mfma_f32_16x16x32_bf16 v[62:65], v[218:221], v[202:205], v[62:65]
	s_waitcnt lgkmcnt(7)
	v_mfma_f32_16x16x32_bf16 v[18:21], v[214:217], v[206:209], v[18:21]
	v_mfma_f32_16x16x32_bf16 v[26:29], v[218:221], v[206:209], v[26:29]
	s_waitcnt vmcnt(10)
	ds_write_b128 v146, v[114:117] offset:27664
	ds_write_b128 v146, v[118:121] offset:64528
	s_waitcnt lgkmcnt(8)
	v_mfma_f32_16x16x32_bf16 v[22:25], v[214:217], v[210:213], v[22:25]
	v_mfma_f32_16x16x32_bf16 v[30:33], v[218:221], v[210:213], v[30:33]
	s_waitcnt lgkmcnt(7)
	v_mfma_f32_16x16x32_bf16 v[34:37], v[222:225], v[198:201], v[34:37]
	v_mfma_f32_16x16x32_bf16 v[38:41], v[222:225], v[202:205], v[38:41]
	s_waitcnt vmcnt(8)
	ds_write_b128 v146, v[122:125] offset:32272
	ds_write_b128 v147, v[126:129] offset:32256
	v_mfma_f32_16x16x32_bf16 v[2:5], v[222:225], v[206:209], v[2:5]
	v_mfma_f32_16x16x32_bf16 v[6:9], v[222:225], v[210:213], v[6:9]
	s_waitcnt lgkmcnt(8)
	v_mfma_f32_16x16x32_bf16 v[42:45], v[226:229], v[198:201], v[42:45]
	v_mfma_f32_16x16x32_bf16 v[46:49], v[226:229], v[202:205], v[46:49]
	v_mfma_f32_16x16x32_bf16 v[10:13], v[226:229], v[206:209], v[10:13]
	v_mfma_f32_16x16x32_bf16 v[14:17], v[226:229], v[210:213], v[14:17]
	s_waitcnt lgkmcnt(0)
	s_barrier
	global_load_dwordx4 v[98:101], v194, s[100:101] offset:384
	global_load_dwordx4 v[102:105], v190, s[98:99] offset:384
	global_load_dwordx4 v[106:109], v195, s[100:101] offset:384
	global_load_dwordx4 v[110:113], v191, s[98:99] offset:384
	global_load_dwordx4 v[114:117], v196, s[100:101] offset:384
	global_load_dwordx4 v[118:121], v192, s[98:99] offset:384
	global_load_dwordx4 v[122:125], v197, s[100:101] offset:384
	global_load_dwordx4 v[126:129], v193, s[98:99] offset:384
	ds_read_b128 v[170:173], v150 offset:55312
	ds_read_b128 v[154:157], v149 offset:18448
	ds_read_b128 v[158:161], v149 offset:20752
	ds_read_b128 v[174:177], v150 offset:57616
	ds_read_b128 v[162:165], v149 offset:23056
	ds_read_b128 v[166:169], v149 offset:25360
	ds_read_b128 v[178:181], v150 offset:59920
	ds_read_b128 v[182:185], v150 offset:62224
	s_waitcnt lgkmcnt(6)
	v_mfma_f32_16x16x32_bf16 v[50:53], v[170:173], v[154:157], v[50:53]
	s_waitcnt lgkmcnt(5)
	v_mfma_f32_16x16x32_bf16 v[54:57], v[170:173], v[158:161], v[54:57]
	s_waitcnt lgkmcnt(4)
	v_mfma_f32_16x16x32_bf16 v[58:61], v[174:177], v[154:157], v[58:61]
	v_mfma_f32_16x16x32_bf16 v[62:65], v[174:177], v[158:161], v[62:65]
	ds_read_b128 v[214:217], v150 offset:55376
	ds_read_b128 v[198:201], v149 offset:18512
	ds_read_b128 v[202:205], v149 offset:20816
	ds_read_b128 v[218:221], v150 offset:57680
	s_waitcnt lgkmcnt(7)
	v_mfma_f32_16x16x32_bf16 v[18:21], v[170:173], v[162:165], v[18:21]
	v_mfma_f32_16x16x32_bf16 v[26:29], v[174:177], v[162:165], v[26:29]
	s_waitcnt lgkmcnt(6)
; #define MFMA(a, b, c) __builtin_amdgcn_mfma_f32_32x32x16_bf16((a), (b), (c), 0, 0, 0)
; template <bool SWAP, class Epi>
; DI void gemm_tile(const u16* __restrict__ A, int lda, const u16* __restrict__ Bt, int ldb, int K, int m0, int n0, char* smem, Epi&& epi) {
;     ...
;   auto compute = [&](int buf) __attribute__((always_inline)) {
;     bf16x8 af[2][2], bfr[2][2];
;     af[0][0] = *(const bf16x8*)(Asb + buf * 128 * 72);
;     af[0][1] = *(const bf16x8*)(Asb + buf * 128 * 72 + 32 * 72);
;     bfr[0][0] = *(const bf16x8*)(Bsb + buf * 128 * 72);
;     bfr[0][1] = *(const bf16x8*)(Bsb + buf * 128 * 72 + 32 * 72);
; #pragma unroll
;     for (int ks = 0; ks < 4; ++ks) {
;       const int c = ks & 1, n = c ^ 1;
;       if (ks < 3) {
;         af[n][0] = *(const bf16x8*)(Asb + buf * 128 * 72 + (ks + 1) * 16);
;         af[n][1] = *(const bf16x8*)(Asb + buf * 128 * 72 + 32 * 72 + (ks + 1) * 16);
;         bfr[n][0] = *(const bf16x8*)(Bsb + buf * 128 * 72 + (ks + 1) * 16);
;         bfr[n][1] = *(const bf16x8*)(Bsb + buf * 128 * 72 + 32 * 72 + (ks + 1) * 16);
;       }
;       __builtin_amdgcn_sched_barrier(0);
; #pragma unroll
;       for (int mi = 0; mi < 2; ++mi)
; #pragma unroll
;         for (int ni = 0; ni < 2; ++ni) {
;           if (SWAP) acc[mi][ni] = MFMA(bfr[c][ni], af[c][mi], acc[mi][ni]);
;           else acc[mi][ni] = MFMA(af[c][mi], bfr[c][ni], acc[mi][ni]);
;         }
;       __builtin_amdgcn_sched_barrier(0);
;     }
;   };
;   for (int kt = 0; kt < KT; kt += 2) {
;     if (kt + 2 < KT) {
;       const int k0 = (kt + 2) << 6;
; #pragma unroll
;       for (int i = 0; i < 4; ++i) { ra0[i] = *(const u32x4*)(ag + (size_t)i * 32 * lda + k0); rb0[i] = *(const u32x4*)(bg + (size_t)i * 32 * ldb + k0); }
;     }
;     compute(0);
; #pragma unroll
;     for (int i = 0; i < 4; ++i) { *(u32x4*)(asw + 128 * 72 + 32 * i * 72) = ra1[i]; *(u32x4*)(bsw + 128 * 72 + 32 * i * 72) = rb1[i]; }
;     __syncthreads();
;     if (kt + 3 < KT) {
;       const int k0 = (kt + 3) << 6;
; #pragma unroll
;       for (int i = 0; i < 4; ++i) { ra1[i] = *(const u32x4*)(ag + (size_t)i * 32 * lda + k0); rb1[i] = *(const u32x4*)(bg + (size_t)i * 32 * ldb + k0); }
;     }
;     compute(1);
;     if (kt + 2 < KT) {
; #pragma unroll
;       for (int i = 0; i < 4; ++i) { *(u32x4*)(asw + 32 * i * 72) = ra0[i]; *(u32x4*)(bsw + 32 * i * 72) = rb0[i]; }
;     }
;     __syncthreads();
;   }
	v_mfma_f32_16x16x32_bf16 v[22:25], v[170:173], v[166:169], v[22:25]
	v_mfma_f32_16x16x32_bf16 v[30:33], v[174:177], v[166:169], v[30:33]
	ds_read_b128 v[206:209], v149 offset:23120
	ds_read_b128 v[210:213], v149 offset:25424
	ds_read_b128 v[222:225], v150 offset:59984
	ds_read_b128 v[226:229], v150 offset:62288
	s_waitcnt lgkmcnt(9)
	v_mfma_f32_16x16x32_bf16 v[34:37], v[178:181], v[154:157], v[34:37]
	v_mfma_f32_16x16x32_bf16 v[38:41], v[178:181], v[158:161], v[38:41]
	v_mfma_f32_16x16x32_bf16 v[2:5], v[178:181], v[162:165], v[2:5]
	v_mfma_f32_16x16x32_bf16 v[6:9], v[178:181], v[166:169], v[6:9]
	s_waitcnt lgkmcnt(8)
	v_mfma_f32_16x16x32_bf16 v[42:45], v[182:185], v[154:157], v[42:45]
	v_mfma_f32_16x16x32_bf16 v[46:49], v[182:185], v[158:161], v[46:49]
	s_waitcnt vmcnt(14)
	ds_write_b128 v146, v[66:69] offset:16
	ds_write_b128 v146, v[70:73] offset:36880
	v_mfma_f32_16x16x32_bf16 v[10:13], v[182:185], v[162:165], v[10:13]
	v_mfma_f32_16x16x32_bf16 v[14:17], v[182:185], v[166:169], v[14:17]
	s_waitcnt lgkmcnt(8)
	v_mfma_f32_16x16x32_bf16 v[50:53], v[214:217], v[198:201], v[50:53]
	s_waitcnt lgkmcnt(7)
	v_mfma_f32_16x16x32_bf16 v[54:57], v[214:217], v[202:205], v[54:57]
	s_waitcnt vmcnt(12)
	ds_write_b128 v146, v[74:77] offset:4624
	ds_write_b128 v146, v[78:81] offset:41488
	s_waitcnt lgkmcnt(8)
	v_mfma_f32_16x16x32_bf16 v[58:61], v[218:221], v[198:201], v[58:61]
	v_mfma_f32_16x16x32_bf16 v[62:65], v[218:221], v[202:205], v[62:65]
	s_waitcnt lgkmcnt(7)
	v_mfma_f32_16x16x32_bf16 v[18:21], v[214:217], v[206:209], v[18:21]
	v_mfma_f32_16x16x32_bf16 v[26:29], v[218:221], v[206:209], v[26:29]
	s_waitcnt vmcnt(10)
	ds_write_b128 v146, v[82:85] offset:9232
	ds_write_b128 v146, v[86:89] offset:46096
	s_waitcnt lgkmcnt(8)
	v_mfma_f32_16x16x32_bf16 v[22:25], v[214:217], v[210:213], v[22:25]
	v_mfma_f32_16x16x32_bf16 v[30:33], v[218:221], v[210:213], v[30:33]
	s_waitcnt lgkmcnt(7)
	v_mfma_f32_16x16x32_bf16 v[34:37], v[222:225], v[198:201], v[34:37]
	v_mfma_f32_16x16x32_bf16 v[38:41], v[222:225], v[202:205], v[38:41]
	s_waitcnt vmcnt(8)
	ds_write_b128 v146, v[90:93] offset:13840
	ds_write_b128 v146, v[94:97] offset:50704
	v_mfma_f32_16x16x32_bf16 v[2:5], v[222:225], v[206:209], v[2:5]
	v_mfma_f32_16x16x32_bf16 v[6:9], v[222:225], v[210:213], v[6:9]
	s_waitcnt lgkmcnt(8)
	v_mfma_f32_16x16x32_bf16 v[42:45], v[226:229], v[198:201], v[42:45]
	v_mfma_f32_16x16x32_bf16 v[46:49], v[226:229], v[202:205], v[46:49]
	v_mfma_f32_16x16x32_bf16 v[10:13], v[226:229], v[206:209], v[10:13]
	v_mfma_f32_16x16x32_bf16 v[14:17], v[226:229], v[210:213], v[14:17]
	s_add_i32 s24, s24, 2
	s_add_u32 s98, s98, 256
	s_addc_u32 s99, s99, 0
	s_add_u32 s100, s100, 256
	s_addc_u32 s101, s101, 0
	s_waitcnt lgkmcnt(0)
	s_barrier
	s_cmp_lt_u32 s24, 30
	s_cbranch_scc1 .LBB0_387
	ds_read_b128 v[170:173], v150 offset:36880
	ds_read_b128 v[154:157], v149 offset:16
	ds_read_b128 v[158:161], v149 offset:2320
	ds_read_b128 v[174:177], v150 offset:39184
	ds_read_b128 v[162:165], v149 offset:4624
	ds_read_b128 v[166:169], v149 offset:6928
	ds_read_b128 v[178:181], v150 offset:41488
	ds_read_b128 v[182:185], v150 offset:43792
	s_waitcnt lgkmcnt(6)
	v_mfma_f32_16x16x32_bf16 v[50:53], v[170:173], v[154:157], v[50:53]
	s_waitcnt lgkmcnt(5)
	v_mfma_f32_16x16x32_bf16 v[54:57], v[170:173], v[158:161], v[54:57]
	s_waitcnt lgkmcnt(4)
	v_mfma_f32_16x16x32_bf16 v[58:61], v[174:177], v[154:157], v[58:61]
	v_mfma_f32_16x16x32_bf16 v[62:65], v[174:177], v[158:161], v[62:65]
	ds_read_b128 v[214:217], v150 offset:36944
	ds_read_b128 v[198:201], v149 offset:80
	ds_read_b128 v[202:205], v149 offset:2384
	ds_read_b128 v[218:221], v150 offset:39248
	s_waitcnt lgkmcnt(7)
	v_mfma_f32_16x16x32_bf16 v[18:21], v[170:173], v[162:165], v[18:21]
	v_mfma_f32_16x16x32_bf16 v[26:29], v[174:177], v[162:165], v[26:29]
	s_waitcnt lgkmcnt(6)
	v_mfma_f32_16x16x32_bf16 v[22:25], v[170:173], v[166:169], v[22:25]
	v_mfma_f32_16x16x32_bf16 v[30:33], v[174:177], v[166:169], v[30:33]
	ds_read_b128 v[206:209], v149 offset:4688
	ds_read_b128 v[210:213], v149 offset:6992
	ds_read_b128 v[222:225], v150 offset:41552
	ds_read_b128 v[226:229], v150 offset:43856
	s_waitcnt lgkmcnt(9)
	v_mfma_f32_16x16x32_bf16 v[34:37], v[178:181], v[154:157], v[34:37]
	v_mfma_f32_16x16x32_bf16 v[38:41], v[178:181], v[158:161], v[38:41]
	v_mfma_f32_16x16x32_bf16 v[2:5], v[178:181], v[162:165], v[2:5]
	v_mfma_f32_16x16x32_bf16 v[6:9], v[178:181], v[166:169], v[6:9]
	s_waitcnt lgkmcnt(8)
	v_mfma_f32_16x16x32_bf16 v[42:45], v[182:185], v[154:157], v[42:45]
	v_mfma_f32_16x16x32_bf16 v[46:49], v[182:185], v[158:161], v[46:49]
	s_waitcnt vmcnt(6)
	ds_write_b128 v146, v[98:101] offset:18448
	ds_write_b128 v146, v[102:105] offset:55312
	v_mfma_f32_16x16x32_bf16 v[10:13], v[182:185], v[162:165], v[10:13]
	v_mfma_f32_16x16x32_bf16 v[14:17], v[182:185], v[166:169], v[14:17]
	s_waitcnt lgkmcnt(8)
	v_mfma_f32_16x16x32_bf16 v[50:53], v[214:217], v[198:201], v[50:53]
	s_waitcnt lgkmcnt(7)
	v_mfma_f32_16x16x32_bf16 v[54:57], v[214:217], v[202:205], v[54:57]
	s_waitcnt vmcnt(4)
	ds_write_b128 v146, v[106:109] offset:23056
	ds_write_b128 v146, v[110:113] offset:59920
	s_waitcnt lgkmcnt(8)
	v_mfma_f32_16x16x32_bf16 v[58:61], v[218:221], v[198:201], v[58:61]
	v_mfma_f32_16x16x32_bf16 v[62:65], v[218:221], v[202:205], v[62:65]
	s_waitcnt lgkmcnt(7)
	v_mfma_f32_16x16x32_bf16 v[18:21], v[214:217], v[206:209], v[18:21]
	v_mfma_f32_16x16x32_bf16 v[26:29], v[218:221], v[206:209], v[26:29]
	s_waitcnt vmcnt(2)
	ds_write_b128 v146, v[114:117] offset:27664
	ds_write_b128 v146, v[118:121] offset:64528
	s_waitcnt lgkmcnt(8)
	v_mfma_f32_16x16x32_bf16 v[22:25], v[214:217], v[210:213], v[22:25]
	v_mfma_f32_16x16x32_bf16 v[30:33], v[218:221], v[210:213], v[30:33]
	s_waitcnt lgkmcnt(7)
	v_mfma_f32_16x16x32_bf16 v[34:37], v[222:225], v[198:201], v[34:37]
	v_mfma_f32_16x16x32_bf16 v[38:41], v[222:225], v[202:205], v[38:41]
	s_waitcnt vmcnt(0)
	ds_write_b128 v146, v[122:125] offset:32272
	ds_write_b128 v147, v[126:129] offset:32256
	v_mfma_f32_16x16x32_bf16 v[2:5], v[222:225], v[206:209], v[2:5]
	v_mfma_f32_16x16x32_bf16 v[6:9], v[222:225], v[210:213], v[6:9]
	s_waitcnt lgkmcnt(8)
	v_mfma_f32_16x16x32_bf16 v[42:45], v[226:229], v[198:201], v[42:45]
	v_mfma_f32_16x16x32_bf16 v[46:49], v[226:229], v[202:205], v[46:49]
	v_mfma_f32_16x16x32_bf16 v[10:13], v[226:229], v[206:209], v[10:13]
	v_mfma_f32_16x16x32_bf16 v[14:17], v[226:229], v[210:213], v[14:17]
	s_waitcnt lgkmcnt(0)
	s_barrier
; #define MFMA(a, b, c) __builtin_amdgcn_mfma_f32_32x32x16_bf16((a), (b), (c), 0, 0, 0)
; template <bool SWAP, class Epi>
; DI void gemm_tile(const u16* __restrict__ A, int lda, const u16* __restrict__ Bt, int ldb, int K, int m0, int n0, char* smem, Epi&& epi) {
;     ...
;   auto compute = [&](int buf) __attribute__((always_inline)) {
;     bf16x8 af[2][2], bfr[2][2];
;     af[0][0] = *(const bf16x8*)(Asb + buf * 128 * 72);
;     af[0][1] = *(const bf16x8*)(Asb + buf * 128 * 72 + 32 * 72);
;     bfr[0][0] = *(const bf16x8*)(Bsb + buf * 128 * 72);
;     bfr[0][1] = *(const bf16x8*)(Bsb + buf * 128 * 72 + 32 * 72);
; #pragma unroll
;     for (int ks = 0; ks < 4; ++ks) {
;       const int c = ks & 1, n = c ^ 1;
;       if (ks < 3) {
;         af[n][0] = *(const bf16x8*)(Asb + buf * 128 * 72 + (ks + 1) * 16);
;         af[n][1] = *(const bf16x8*)(Asb + buf * 128 * 72 + 32 * 72 + (ks + 1) * 16);
;         bfr[n][0] = *(const bf16x8*)(Bsb + buf * 128 * 72 + (ks + 1) * 16);
;         bfr[n][1] = *(const bf16x8*)(Bsb + buf * 128 * 72 + 32 * 72 + (ks + 1) * 16);
;       }
;       __builtin_amdgcn_sched_barrier(0);
; #pragma unroll
;       for (int mi = 0; mi < 2; ++mi)
; #pragma unroll
;         for (int ni = 0; ni < 2; ++ni) {
;           if (SWAP) acc[mi][ni] = MFMA(bfr[c][ni], af[c][mi], acc[mi][ni]);
;           else acc[mi][ni] = MFMA(af[c][mi], bfr[c][ni], acc[mi][ni]);
;         }
;       __builtin_amdgcn_sched_barrier(0);
;     }
;   };
;     ...
;     compute(1);
;     if (kt + 2 < KT) {
; #pragma unroll
;       for (int i = 0; i < 4; ++i) { *(u32x4*)(asw + 32 * i * 72) = ra0[i]; *(u32x4*)(bsw + 32 * i * 72) = rb0[i]; }
;     }
;     __syncthreads();
	ds_read_b128 v[170:173], v150 offset:55312
	ds_read_b128 v[154:157], v149 offset:18448
	ds_read_b128 v[158:161], v149 offset:20752
	ds_read_b128 v[174:177], v150 offset:57616
	ds_read_b128 v[162:165], v149 offset:23056
	ds_read_b128 v[166:169], v149 offset:25360
	ds_read_b128 v[178:181], v150 offset:59920
	ds_read_b128 v[182:185], v150 offset:62224
	s_waitcnt lgkmcnt(6)
	v_mfma_f32_16x16x32_bf16 v[50:53], v[170:173], v[154:157], v[50:53]
	s_waitcnt lgkmcnt(5)
	v_mfma_f32_16x16x32_bf16 v[54:57], v[170:173], v[158:161], v[54:57]
	s_waitcnt lgkmcnt(4)
	v_mfma_f32_16x16x32_bf16 v[58:61], v[174:177], v[154:157], v[58:61]
	v_mfma_f32_16x16x32_bf16 v[62:65], v[174:177], v[158:161], v[62:65]
	ds_read_b128 v[214:217], v150 offset:55376
	ds_read_b128 v[198:201], v149 offset:18512
	ds_read_b128 v[202:205], v149 offset:20816
	ds_read_b128 v[218:221], v150 offset:57680
	s_waitcnt lgkmcnt(7)
	v_mfma_f32_16x16x32_bf16 v[18:21], v[170:173], v[162:165], v[18:21]
	v_mfma_f32_16x16x32_bf16 v[26:29], v[174:177], v[162:165], v[26:29]
	s_waitcnt lgkmcnt(6)
	v_mfma_f32_16x16x32_bf16 v[22:25], v[170:173], v[166:169], v[22:25]
	v_mfma_f32_16x16x32_bf16 v[30:33], v[174:177], v[166:169], v[30:33]
	ds_read_b128 v[206:209], v149 offset:23120
	ds_read_b128 v[210:213], v149 offset:25424
	ds_read_b128 v[222:225], v150 offset:59984
	ds_read_b128 v[226:229], v150 offset:62288
	s_waitcnt lgkmcnt(9)
	v_mfma_f32_16x16x32_bf16 v[34:37], v[178:181], v[154:157], v[34:37]
	v_mfma_f32_16x16x32_bf16 v[38:41], v[178:181], v[158:161], v[38:41]
	v_mfma_f32_16x16x32_bf16 v[2:5], v[178:181], v[162:165], v[2:5]
	v_mfma_f32_16x16x32_bf16 v[6:9], v[178:181], v[166:169], v[6:9]
	s_waitcnt lgkmcnt(8)
	v_mfma_f32_16x16x32_bf16 v[42:45], v[182:185], v[154:157], v[42:45]
	v_mfma_f32_16x16x32_bf16 v[46:49], v[182:185], v[158:161], v[46:49]
	v_mfma_f32_16x16x32_bf16 v[10:13], v[182:185], v[162:165], v[10:13]
	v_mfma_f32_16x16x32_bf16 v[14:17], v[182:185], v[166:169], v[14:17]
	s_waitcnt lgkmcnt(6)
	v_mfma_f32_16x16x32_bf16 v[50:53], v[214:217], v[198:201], v[50:53]
	s_waitcnt lgkmcnt(5)
	v_mfma_f32_16x16x32_bf16 v[54:57], v[214:217], v[202:205], v[54:57]
	s_waitcnt lgkmcnt(4)
	v_mfma_f32_16x16x32_bf16 v[58:61], v[218:221], v[198:201], v[58:61]
	v_mfma_f32_16x16x32_bf16 v[62:65], v[218:221], v[202:205], v[62:65]
	s_waitcnt lgkmcnt(3)
	v_mfma_f32_16x16x32_bf16 v[18:21], v[214:217], v[206:209], v[18:21]
	v_mfma_f32_16x16x32_bf16 v[26:29], v[218:221], v[206:209], v[26:29]
	s_waitcnt lgkmcnt(2)
	v_mfma_f32_16x16x32_bf16 v[22:25], v[214:217], v[210:213], v[22:25]
	v_mfma_f32_16x16x32_bf16 v[30:33], v[218:221], v[210:213], v[30:33]
	s_waitcnt lgkmcnt(1)
	v_mfma_f32_16x16x32_bf16 v[34:37], v[222:225], v[198:201], v[34:37]
	v_mfma_f32_16x16x32_bf16 v[38:41], v[222:225], v[202:205], v[38:41]
	v_mfma_f32_16x16x32_bf16 v[2:5], v[222:225], v[206:209], v[2:5]
	v_mfma_f32_16x16x32_bf16 v[6:9], v[222:225], v[210:213], v[6:9]
	s_waitcnt lgkmcnt(0)
	v_mfma_f32_16x16x32_bf16 v[42:45], v[226:229], v[198:201], v[42:45]
	v_mfma_f32_16x16x32_bf16 v[46:49], v[226:229], v[202:205], v[46:49]
	v_mfma_f32_16x16x32_bf16 v[10:13], v[226:229], v[206:209], v[10:13]
	v_mfma_f32_16x16x32_bf16 v[14:17], v[226:229], v[210:213], v[14:17]
	s_nop 7
	s_nop 7
	v_permlane16_swap_b32_e32 v50, v54
	v_permlane16_swap_b32_e32 v51, v55
	v_permlane16_swap_b32_e32 v52, v56
	v_permlane16_swap_b32_e32 v53, v57
	v_permlane16_swap_b32_e32 v58, v62
	v_permlane16_swap_b32_e32 v59, v63
	v_permlane16_swap_b32_e32 v60, v64
	v_permlane16_swap_b32_e32 v61, v65
	v_permlane16_swap_b32_e32 v34, v38
	v_permlane16_swap_b32_e32 v35, v39
	v_permlane16_swap_b32_e32 v36, v40
	v_permlane16_swap_b32_e32 v37, v41
	v_permlane16_swap_b32_e32 v42, v46
	v_permlane16_swap_b32_e32 v43, v47
	v_permlane16_swap_b32_e32 v44, v48
	v_permlane16_swap_b32_e32 v45, v49
	v_permlane16_swap_b32_e32 v18, v22
	v_permlane16_swap_b32_e32 v19, v23
	v_permlane16_swap_b32_e32 v20, v24
	v_permlane16_swap_b32_e32 v21, v25
	v_permlane16_swap_b32_e32 v26, v30
	v_permlane16_swap_b32_e32 v27, v31
	v_permlane16_swap_b32_e32 v28, v32
	v_permlane16_swap_b32_e32 v29, v33
	v_permlane16_swap_b32_e32 v2, v6
	v_permlane16_swap_b32_e32 v3, v7
	v_permlane16_swap_b32_e32 v4, v8
	v_permlane16_swap_b32_e32 v5, v9
	v_permlane16_swap_b32_e32 v10, v14
	v_permlane16_swap_b32_e32 v11, v15
	v_permlane16_swap_b32_e32 v12, v16
	v_permlane16_swap_b32_e32 v13, v17
	s_waitcnt lgkmcnt(0)
	s_barrier
	s_branch .LBB0_393

; template <bool SWAP, class Epi>
; DI void gemm_tile(const u16* __restrict__ A, int lda, const u16* __restrict__ Bt, int ldb, int K, int m0, int n0, char* smem, Epi&& epi) {
;     ...
;   const int tid = threadIdx.x, lane = tid & 63, w = tid >> 6, wm = w >> 1, wn = w & 1;
;   const int r = lane & 31, hi = lane >> 5;
;   f32x16 acc[2][2];
; #pragma unroll
;   for (int a = 0; a < 2; ++a)
; #pragma unroll
;     for (int b = 0; b < 2; ++b)
; #pragma unroll
;       for (int i = 0; i < 16; ++i) acc[a][b][i] = 0.f;
;   const int srow = tid >> 3, skc = tid & 7;
;   const u16* ag = A + (size_t)(m0 + srow) * lda + skc * 8;
;   const u16* bg = Bt + (size_t)(n0 + srow) * ldb + skc * 8;
;   u16* asw = As + srow * 72 + skc * 8;
;   u16* bsw = Bs + srow * 72 + skc * 8;
;   u32x4 ra0[4], rb0[4], ra1[4], rb1[4];
; #pragma unroll
;   for (int i = 0; i < 4; ++i) { ra0[i] = *(const u32x4*)(ag + (size_t)i * 32 * lda); rb0[i] = *(const u32x4*)(bg + (size_t)i * 32 * ldb); }
; #pragma unroll
;   for (int i = 0; i < 4; ++i) { ra1[i] = *(const u32x4*)(ag + (size_t)i * 32 * lda + 64); rb1[i] = *(const u32x4*)(bg + (size_t)i * 32 * ldb + 64); }
;   __syncthreads();
; #pragma unroll
;   for (int i = 0; i < 4; ++i) { *(u32x4*)(asw + 32 * i * 72) = ra0[i]; *(u32x4*)(bsw + 32 * i * 72) = rb0[i]; }
;   __syncthreads();
;   const int KT = K >> 6;
;   const u16* Asb = As + (wm * 64 + r) * 72 + hi * 8;
;   const u16* Bsb = Bs + (wn * 64 + r) * 72 + hi * 8;
; DI void phase5(const Params& p, char* smem) {
;     ...
;   for (int it = blockIdx.x; it < 64 * 16; it += gridDim.x) {
;     const int tn = it / 64, tm = it % 64;
;     gemm_tile<true>(MG, D_, W, D_, D_, tm * 128, tn * 128, smem, [&](f32x16 (&acc)[2][2], int mb, int nb, int r, int hi) __attribute__((always_inline)) {
.Lprio_p5:
	s_cmpk_gt_i32 s12, 0x3ff
	s_cbranch_scc1 .LBB0_754
	s_waitcnt lgkmcnt(0)
	v_lshlrev_b32_e32 v2, 4, v0
	v_and_b32_e32 v130, 0x70, v2
	v_mov_b32_e32 v131, 0
	v_lshl_add_u64 v[2:3], s[82:83], 0, v[130:131]
	s_mov_b64 s[4:5], 0x10638000
	v_lshrrev_b32_e32 v1, 3, v0
	s_waitcnt vmcnt(9)
	v_lshl_add_u64 v[132:133], v[2:3], 0, s[4:5]
	s_mov_b64 s[4:5], 0x14b8000
	v_lshl_add_u64 v[134:135], v[2:3], 0, s[4:5]
	v_mul_u32_u24_e32 v2, 0x48, v1
	v_and_b32_e32 v4, 31, v0
	v_lshlrev_b32_e32 v2, 1, v2
	v_lshrrev_b32_e32 v3, 1, v0
	s_waitcnt vmcnt(6)
	v_add3_u32 v144, 0, v2, v130
	v_bfe_u32 v2, v0, 5, 1
	v_and_or_b32 v146, v3, 64, v4
	v_mul_u32_u24_e32 v3, 0x90, v146
	v_lshlrev_b32_e32 v4, 4, v2
	v_add3_u32 v147, 0, v3, v4
	v_and_b32_e32 v3, 0x5f, v0
	s_load_dword s13, s[0:1], 0xc0
	v_mul_u32_u24_e32 v3, 0x90, v3
	s_waitcnt vmcnt(5)
	v_add3_u32 v148, 0, v3, v4
	v_and_b32_e32 v3, 64, v0
	s_add_u32 s2, s82, 0x12638000
	v_lshl_or_b32 v149, v2, 2, v3
	v_and_b32_e32 v2, 7, v0
	s_addc_u32 s3, s83, 0
	v_add_u32_e32 v145, 0x9010, v144
	v_lshlrev_b32_e32 v130, 4, v2
	s_mov_b32 s14, 0x20000
	s_mov_b32 s15, 0x40000
	s_mov_b32 s16, 0x60000
	s_mov_b64 s[4:5], 0x100
	s_mov_b64 s[6:7], 0xc000
	s_mov_b32 s17, s12
	v_lshrrev_b32_e32 v198, 3, v0
	v_lshrrev_b32_e32 v199, 2, v198
	v_lshrrev_b32_e32 v200, 3, v198
	v_xor_b32_e32 v199, v199, v200
	v_and_b32_e32 v199, 1, v199
	v_and_b32_e32 v200, 1, v0
	v_lshlrev_b32_e32 v200, 5, v200
	v_sub_u32_e32 v200, 16, v200
	v_mul_lo_u32 v199, v199, v200
	v_add_u32_e32 v144, v144, v199
	v_add_u32_e32 v145, v145, v199
	v_and_b32_e32 v198, 15, v0
	v_bfe_u32 v199, v0, 4, 2
	v_lshrrev_b32_e32 v200, 2, v198
	v_lshrrev_b32_e32 v201, 3, v198
	v_xor_b32_e32 v200, v200, v201
	v_and_b32_e32 v200, 1, v200
	v_xor_b32_e32 v199, v199, v200
	v_lshlrev_b32_e32 v199, 4, v199
	v_bfe_u32 v200, v0, 7, 1
	v_lshl_or_b32 v200, v200, 6, v198
	v_mul_u32_u24_e32 v200, 0x90, v200
	v_add_u32_e32 v147, v200, v199
	v_and_b32_e32 v201, 3, v198
	v_and_b32_e32 v202, 4, v198
	v_lshlrev_b32_e32 v202, 1, v202
	v_and_b32_e32 v203, 8, v198
	v_lshrrev_b32_e32 v203, 1, v203
	v_or3_b32 v198, v201, v202, v203
	v_bfe_u32 v200, v0, 6, 1
	v_lshl_or_b32 v200, v200, 6, v198
	v_mul_u32_u24_e32 v200, 0x90, v200
	v_add_u32_e32 v148, v200, v199
	s_branch .LBB0_746

; #define MFMA(a, b, c) __builtin_amdgcn_mfma_f32_32x32x16_bf16((a), (b), (c), 0, 0, 0)
; template <bool SWAP, class Epi>
; DI void gemm_tile(const u16* __restrict__ A, int lda, const u16* __restrict__ Bt, int ldb, int K, int m0, int n0, char* smem, Epi&& epi) {
;     ...
;   auto compute = [&](int buf) __attribute__((always_inline)) {
;     bf16x8 af[2][2], bfr[2][2];
;     af[0][0] = *(const bf16x8*)(Asb + buf * 128 * 72);
;     af[0][1] = *(const bf16x8*)(Asb + buf * 128 * 72 + 32 * 72);
;     bfr[0][0] = *(const bf16x8*)(Bsb + buf * 128 * 72);
;     bfr[0][1] = *(const bf16x8*)(Bsb + buf * 128 * 72 + 32 * 72);
; #pragma unroll
;     for (int ks = 0; ks < 4; ++ks) {
;       const int c = ks & 1, n = c ^ 1;
;       if (ks < 3) {
;         af[n][0] = *(const bf16x8*)(Asb + buf * 128 * 72 + (ks + 1) * 16);
;         af[n][1] = *(const bf16x8*)(Asb + buf * 128 * 72 + 32 * 72 + (ks + 1) * 16);
;         bfr[n][0] = *(const bf16x8*)(Bsb + buf * 128 * 72 + (ks + 1) * 16);
;         bfr[n][1] = *(const bf16x8*)(Bsb + buf * 128 * 72 + 32 * 72 + (ks + 1) * 16);
;       }
;       __builtin_amdgcn_sched_barrier(0);
; #pragma unroll
;       for (int mi = 0; mi < 2; ++mi)
; #pragma unroll
;         for (int ni = 0; ni < 2; ++ni) {
;           if (SWAP) acc[mi][ni] = MFMA(bfr[c][ni], af[c][mi], acc[mi][ni]);
;           else acc[mi][ni] = MFMA(af[c][mi], bfr[c][ni], acc[mi][ni]);
;         }
;       __builtin_amdgcn_sched_barrier(0);
;     }
;   };
;   for (int kt = 0; kt < KT; kt += 2) {
;     if (kt + 2 < KT) {
;       const int k0 = (kt + 2) << 6;
; #pragma unroll
;       for (int i = 0; i < 4; ++i) { ra0[i] = *(const u32x4*)(ag + (size_t)i * 32 * lda + k0); rb0[i] = *(const u32x4*)(bg + (size_t)i * 32 * ldb + k0); }
;     }
;     compute(0);
; #pragma unroll
;     for (int i = 0; i < 4; ++i) { *(u32x4*)(asw + 128 * 72 + 32 * i * 72) = ra1[i]; *(u32x4*)(bsw + 128 * 72 + 32 * i * 72) = rb1[i]; }
;     __syncthreads();
;     if (kt + 3 < KT) {
;       const int k0 = (kt + 3) << 6;
; #pragma unroll
;       for (int i = 0; i < 4; ++i) { ra1[i] = *(const u32x4*)(ag + (size_t)i * 32 * lda + k0); rb1[i] = *(const u32x4*)(bg + (size_t)i * 32 * ldb + k0); }
;     }
;     compute(1);
;     if (kt + 2 < KT) {
; #pragma unroll
;       for (int i = 0; i < 4; ++i) { *(u32x4*)(asw + 32 * i * 72) = ra0[i]; *(u32x4*)(bsw + 32 * i * 72) = rb0[i]; }
;     }
;     __syncthreads();
;   }
.LBB0_748:
	global_load_dwordx4 v[66:69], v194, s[100:101] offset:256
	global_load_dwordx4 v[70:73], v190, s[98:99] offset:256
	global_load_dwordx4 v[74:77], v195, s[100:101] offset:256
	global_load_dwordx4 v[78:81], v191, s[98:99] offset:256
	global_load_dwordx4 v[82:85], v196, s[100:101] offset:256
	global_load_dwordx4 v[86:89], v192, s[98:99] offset:256
	global_load_dwordx4 v[90:93], v197, s[100:101] offset:256
	global_load_dwordx4 v[94:97], v193, s[98:99] offset:256
	ds_read_b128 v[166:169], v148 offset:36880
	ds_read_b128 v[150:153], v147 offset:16
	ds_read_b128 v[154:157], v147 offset:2320
	ds_read_b128 v[170:173], v148 offset:39184
	ds_read_b128 v[158:161], v147 offset:4624
	ds_read_b128 v[162:165], v147 offset:6928
	ds_read_b128 v[174:177], v148 offset:41488
	ds_read_b128 v[178:181], v148 offset:43792
	s_waitcnt lgkmcnt(6)
	v_mfma_f32_16x16x32_bf16 v[50:53], v[166:169], v[150:153], v[50:53]
	s_waitcnt lgkmcnt(5)
	v_mfma_f32_16x16x32_bf16 v[54:57], v[166:169], v[154:157], v[54:57]
	s_waitcnt lgkmcnt(4)
	v_mfma_f32_16x16x32_bf16 v[58:61], v[170:173], v[150:153], v[58:61]
	v_mfma_f32_16x16x32_bf16 v[62:65], v[170:173], v[154:157], v[62:65]
	ds_read_b128 v[214:217], v148 offset:36944
	ds_read_b128 v[198:201], v147 offset:80
	ds_read_b128 v[202:205], v147 offset:2384
	ds_read_b128 v[218:221], v148 offset:39248
	s_waitcnt lgkmcnt(7)
	v_mfma_f32_16x16x32_bf16 v[18:21], v[166:169], v[158:161], v[18:21]
	v_mfma_f32_16x16x32_bf16 v[26:29], v[170:173], v[158:161], v[26:29]
	s_waitcnt lgkmcnt(6)
	v_mfma_f32_16x16x32_bf16 v[22:25], v[166:169], v[162:165], v[22:25]
	v_mfma_f32_16x16x32_bf16 v[30:33], v[170:173], v[162:165], v[30:33]
	ds_read_b128 v[206:209], v147 offset:4688
	ds_read_b128 v[210:213], v147 offset:6992
	ds_read_b128 v[222:225], v148 offset:41552
	ds_read_b128 v[226:229], v148 offset:43856
	s_waitcnt lgkmcnt(9)
	v_mfma_f32_16x16x32_bf16 v[34:37], v[174:177], v[150:153], v[34:37]
	v_mfma_f32_16x16x32_bf16 v[38:41], v[174:177], v[154:157], v[38:41]
	v_mfma_f32_16x16x32_bf16 v[2:5], v[174:177], v[158:161], v[2:5]
	v_mfma_f32_16x16x32_bf16 v[6:9], v[174:177], v[162:165], v[6:9]
	s_waitcnt lgkmcnt(8)
	v_mfma_f32_16x16x32_bf16 v[42:45], v[178:181], v[150:153], v[42:45]
	v_mfma_f32_16x16x32_bf16 v[46:49], v[178:181], v[154:157], v[46:49]
	s_waitcnt vmcnt(14)
	ds_write_b128 v144, v[98:101] offset:18448
	ds_write_b128 v144, v[102:105] offset:55312
	v_mfma_f32_16x16x32_bf16 v[10:13], v[178:181], v[158:161], v[10:13]
	v_mfma_f32_16x16x32_bf16 v[14:17], v[178:181], v[162:165], v[14:17]
	s_waitcnt lgkmcnt(8)
	v_mfma_f32_16x16x32_bf16 v[50:53], v[214:217], v[198:201], v[50:53]
	s_waitcnt lgkmcnt(7)
	v_mfma_f32_16x16x32_bf16 v[54:57], v[214:217], v[202:205], v[54:57]
	s_waitcnt vmcnt(12)
	ds_write_b128 v144, v[106:109] offset:23056
	ds_write_b128 v144, v[110:113] offset:59920
	s_waitcnt lgkmcnt(8)
	v_mfma_f32_16x16x32_bf16 v[58:61], v[218:221], v[198:201], v[58:61]
	v_mfma_f32_16x16x32_bf16 v[62:65], v[218:221], v[202:205], v[62:65]
	s_waitcnt lgkmcnt(7)
	v_mfma_f32_16x16x32_bf16 v[18:21], v[214:217], v[206:209], v[18:21]
	v_mfma_f32_16x16x32_bf16 v[26:29], v[218:221], v[206:209], v[26:29]
	s_waitcnt vmcnt(10)
	ds_write_b128 v144, v[114:117] offset:27664
	ds_write_b128 v144, v[118:121] offset:64528
	s_waitcnt lgkmcnt(8)
	v_mfma_f32_16x16x32_bf16 v[22:25], v[214:217], v[210:213], v[22:25]
	v_mfma_f32_16x16x32_bf16 v[30:33], v[218:221], v[210:213], v[30:33]
	s_waitcnt lgkmcnt(7)
	v_mfma_f32_16x16x32_bf16 v[34:37], v[222:225], v[198:201], v[34:37]
	v_mfma_f32_16x16x32_bf16 v[38:41], v[222:225], v[202:205], v[38:41]
	s_waitcnt vmcnt(8)
	ds_write_b128 v144, v[122:125] offset:32272
	ds_write_b128 v145, v[126:129] offset:32256
	v_mfma_f32_16x16x32_bf16 v[2:5], v[222:225], v[206:209], v[2:5]
	v_mfma_f32_16x16x32_bf16 v[6:9], v[222:225], v[210:213], v[6:9]
	s_waitcnt lgkmcnt(8)
	v_mfma_f32_16x16x32_bf16 v[42:45], v[226:229], v[198:201], v[42:45]
	v_mfma_f32_16x16x32_bf16 v[46:49], v[226:229], v[202:205], v[46:49]
	v_mfma_f32_16x16x32_bf16 v[10:13], v[226:229], v[206:209], v[10:13]
	v_mfma_f32_16x16x32_bf16 v[14:17], v[226:229], v[210:213], v[14:17]
	s_waitcnt lgkmcnt(0)
	s_barrier
	global_load_dwordx4 v[98:101], v194, s[100:101] offset:384
	global_load_dwordx4 v[102:105], v190, s[98:99] offset:384
	global_load_dwordx4 v[106:109], v195, s[100:101] offset:384
	global_load_dwordx4 v[110:113], v191, s[98:99] offset:384
	global_load_dwordx4 v[114:117], v196, s[100:101] offset:384
	global_load_dwordx4 v[118:121], v192, s[98:99] offset:384
	global_load_dwordx4 v[122:125], v197, s[100:101] offset:384
	global_load_dwordx4 v[126:129], v193, s[98:99] offset:384
	ds_read_b128 v[166:169], v148 offset:55312
	ds_read_b128 v[150:153], v147 offset:18448
	ds_read_b128 v[154:157], v147 offset:20752
	ds_read_b128 v[170:173], v148 offset:57616
	ds_read_b128 v[158:161], v147 offset:23056
	ds_read_b128 v[162:165], v147 offset:25360
	ds_read_b128 v[174:177], v148 offset:59920
	ds_read_b128 v[178:181], v148 offset:62224
	s_waitcnt lgkmcnt(6)
	v_mfma_f32_16x16x32_bf16 v[50:53], v[166:169], v[150:153], v[50:53]
	s_waitcnt lgkmcnt(5)
	v_mfma_f32_16x16x32_bf16 v[54:57], v[166:169], v[154:157], v[54:57]
	s_waitcnt lgkmcnt(4)
	v_mfma_f32_16x16x32_bf16 v[58:61], v[170:173], v[150:153], v[58:61]
	v_mfma_f32_16x16x32_bf16 v[62:65], v[170:173], v[154:157], v[62:65]
	ds_read_b128 v[214:217], v148 offset:55376
	ds_read_b128 v[198:201], v147 offset:18512
	ds_read_b128 v[202:205], v147 offset:20816
	ds_read_b128 v[218:221], v148 offset:57680
	s_waitcnt lgkmcnt(7)
	v_mfma_f32_16x16x32_bf16 v[18:21], v[166:169], v[158:161], v[18:21]
	v_mfma_f32_16x16x32_bf16 v[26:29], v[170:173], v[158:161], v[26:29]
	s_waitcnt lgkmcnt(6)
; #define MFMA(a, b, c) __builtin_amdgcn_mfma_f32_32x32x16_bf16((a), (b), (c), 0, 0, 0)
; template <bool SWAP, class Epi>
; DI void gemm_tile(const u16* __restrict__ A, int lda, const u16* __restrict__ Bt, int ldb, int K, int m0, int n0, char* smem, Epi&& epi) {
;     ...
;   auto compute = [&](int buf) __attribute__((always_inline)) {
;     bf16x8 af[2][2], bfr[2][2];
;     af[0][0] = *(const bf16x8*)(Asb + buf * 128 * 72);
;     af[0][1] = *(const bf16x8*)(Asb + buf * 128 * 72 + 32 * 72);
;     bfr[0][0] = *(const bf16x8*)(Bsb + buf * 128 * 72);
;     bfr[0][1] = *(const bf16x8*)(Bsb + buf * 128 * 72 + 32 * 72);
; #pragma unroll
;     for (int ks = 0; ks < 4; ++ks) {
;       const int c = ks & 1, n = c ^ 1;
;       if (ks < 3) {
;         af[n][0] = *(const bf16x8*)(Asb + buf * 128 * 72 + (ks + 1) * 16);
;         af[n][1] = *(const bf16x8*)(Asb + buf * 128 * 72 + 32 * 72 + (ks + 1) * 16);
;         bfr[n][0] = *(const bf16x8*)(Bsb + buf * 128 * 72 + (ks + 1) * 16);
;         bfr[n][1] = *(const bf16x8*)(Bsb + buf * 128 * 72 + 32 * 72 + (ks + 1) * 16);
;       }
;       __builtin_amdgcn_sched_barrier(0);
; #pragma unroll
;       for (int mi = 0; mi < 2; ++mi)
; #pragma unroll
;         for (int ni = 0; ni < 2; ++ni) {
;           if (SWAP) acc[mi][ni] = MFMA(bfr[c][ni], af[c][mi], acc[mi][ni]);
;           else acc[mi][ni] = MFMA(af[c][mi], bfr[c][ni], acc[mi][ni]);
;         }
;       __builtin_amdgcn_sched_barrier(0);
;     }
;   };
;   for (int kt = 0; kt < KT; kt += 2) {
;     if (kt + 2 < KT) {
;       const int k0 = (kt + 2) << 6;
; #pragma unroll
;       for (int i = 0; i < 4; ++i) { ra0[i] = *(const u32x4*)(ag + (size_t)i * 32 * lda + k0); rb0[i] = *(const u32x4*)(bg + (size_t)i * 32 * ldb + k0); }
;     }
;     compute(0);
; #pragma unroll
;     for (int i = 0; i < 4; ++i) { *(u32x4*)(asw + 128 * 72 + 32 * i * 72) = ra1[i]; *(u32x4*)(bsw + 128 * 72 + 32 * i * 72) = rb1[i]; }
;     __syncthreads();
;     if (kt + 3 < KT) {
;       const int k0 = (kt + 3) << 6;
; #pragma unroll
;       for (int i = 0; i < 4; ++i) { ra1[i] = *(const u32x4*)(ag + (size_t)i * 32 * lda + k0); rb1[i] = *(const u32x4*)(bg + (size_t)i * 32 * ldb + k0); }
;     }
;     compute(1);
;     if (kt + 2 < KT) {
; #pragma unroll
;       for (int i = 0; i < 4; ++i) { *(u32x4*)(asw + 32 * i * 72) = ra0[i]; *(u32x4*)(bsw + 32 * i * 72) = rb0[i]; }
;     }
;     __syncthreads();
;   }
	v_mfma_f32_16x16x32_bf16 v[22:25], v[166:169], v[162:165], v[22:25]
	v_mfma_f32_16x16x32_bf16 v[30:33], v[170:173], v[162:165], v[30:33]
	ds_read_b128 v[206:209], v147 offset:23120
	ds_read_b128 v[210:213], v147 offset:25424
	ds_read_b128 v[222:225], v148 offset:59984
	ds_read_b128 v[226:229], v148 offset:62288
	s_waitcnt lgkmcnt(9)
	v_mfma_f32_16x16x32_bf16 v[34:37], v[174:177], v[150:153], v[34:37]
	v_mfma_f32_16x16x32_bf16 v[38:41], v[174:177], v[154:157], v[38:41]
	v_mfma_f32_16x16x32_bf16 v[2:5], v[174:177], v[158:161], v[2:5]
	v_mfma_f32_16x16x32_bf16 v[6:9], v[174:177], v[162:165], v[6:9]
	s_waitcnt lgkmcnt(8)
	v_mfma_f32_16x16x32_bf16 v[42:45], v[178:181], v[150:153], v[42:45]
	v_mfma_f32_16x16x32_bf16 v[46:49], v[178:181], v[154:157], v[46:49]
	s_waitcnt vmcnt(14)
	ds_write_b128 v144, v[66:69] offset:16
	ds_write_b128 v144, v[70:73] offset:36880
	v_mfma_f32_16x16x32_bf16 v[10:13], v[178:181], v[158:161], v[10:13]
	v_mfma_f32_16x16x32_bf16 v[14:17], v[178:181], v[162:165], v[14:17]
	s_waitcnt lgkmcnt(8)
	v_mfma_f32_16x16x32_bf16 v[50:53], v[214:217], v[198:201], v[50:53]
	s_waitcnt lgkmcnt(7)
	v_mfma_f32_16x16x32_bf16 v[54:57], v[214:217], v[202:205], v[54:57]
	s_waitcnt vmcnt(12)
	ds_write_b128 v144, v[74:77] offset:4624
	ds_write_b128 v144, v[78:81] offset:41488
	s_waitcnt lgkmcnt(8)
	v_mfma_f32_16x16x32_bf16 v[58:61], v[218:221], v[198:201], v[58:61]
	v_mfma_f32_16x16x32_bf16 v[62:65], v[218:221], v[202:205], v[62:65]
	s_waitcnt lgkmcnt(7)
	v_mfma_f32_16x16x32_bf16 v[18:21], v[214:217], v[206:209], v[18:21]
	v_mfma_f32_16x16x32_bf16 v[26:29], v[218:221], v[206:209], v[26:29]
	s_waitcnt vmcnt(10)
	ds_write_b128 v144, v[82:85] offset:9232
	ds_write_b128 v144, v[86:89] offset:46096
	s_waitcnt lgkmcnt(8)
	v_mfma_f32_16x16x32_bf16 v[22:25], v[214:217], v[210:213], v[22:25]
	v_mfma_f32_16x16x32_bf16 v[30:33], v[218:221], v[210:213], v[30:33]
	s_waitcnt lgkmcnt(7)
	v_mfma_f32_16x16x32_bf16 v[34:37], v[222:225], v[198:201], v[34:37]
	v_mfma_f32_16x16x32_bf16 v[38:41], v[222:225], v[202:205], v[38:41]
	s_waitcnt vmcnt(8)
	ds_write_b128 v144, v[90:93] offset:13840
	ds_write_b128 v144, v[94:97] offset:50704
	v_mfma_f32_16x16x32_bf16 v[2:5], v[222:225], v[206:209], v[2:5]
	v_mfma_f32_16x16x32_bf16 v[6:9], v[222:225], v[210:213], v[6:9]
	s_waitcnt lgkmcnt(8)
	v_mfma_f32_16x16x32_bf16 v[42:45], v[226:229], v[198:201], v[42:45]
	v_mfma_f32_16x16x32_bf16 v[46:49], v[226:229], v[202:205], v[46:49]
	v_mfma_f32_16x16x32_bf16 v[10:13], v[226:229], v[206:209], v[10:13]
	v_mfma_f32_16x16x32_bf16 v[14:17], v[226:229], v[210:213], v[14:17]
	s_add_i32 s20, s20, 2
	s_add_u32 s98, s98, 256
	s_addc_u32 s99, s99, 0
	s_add_u32 s100, s100, 256
	s_addc_u32 s101, s101, 0
	s_waitcnt lgkmcnt(0)
	s_barrier
	s_cmp_lt_u32 s20, 30
	s_cbranch_scc1 .LBB0_748
	ds_read_b128 v[166:169], v148 offset:36880
	ds_read_b128 v[150:153], v147 offset:16
	ds_read_b128 v[154:157], v147 offset:2320
	ds_read_b128 v[170:173], v148 offset:39184
	ds_read_b128 v[158:161], v147 offset:4624
	ds_read_b128 v[162:165], v147 offset:6928
	ds_read_b128 v[174:177], v148 offset:41488
	ds_read_b128 v[178:181], v148 offset:43792
	s_waitcnt lgkmcnt(6)
	v_mfma_f32_16x16x32_bf16 v[50:53], v[166:169], v[150:153], v[50:53]
	s_waitcnt lgkmcnt(5)
	v_mfma_f32_16x16x32_bf16 v[54:57], v[166:169], v[154:157], v[54:57]
	s_waitcnt lgkmcnt(4)
	v_mfma_f32_16x16x32_bf16 v[58:61], v[170:173], v[150:153], v[58:61]
	v_mfma_f32_16x16x32_bf16 v[62:65], v[170:173], v[154:157], v[62:65]
	ds_read_b128 v[214:217], v148 offset:36944
	ds_read_b128 v[198:201], v147 offset:80
	ds_read_b128 v[202:205], v147 offset:2384
	ds_read_b128 v[218:221], v148 offset:39248
	s_waitcnt lgkmcnt(7)
	v_mfma_f32_16x16x32_bf16 v[18:21], v[166:169], v[158:161], v[18:21]
	v_mfma_f32_16x16x32_bf16 v[26:29], v[170:173], v[158:161], v[26:29]
	s_waitcnt lgkmcnt(6)
	v_mfma_f32_16x16x32_bf16 v[22:25], v[166:169], v[162:165], v[22:25]
	v_mfma_f32_16x16x32_bf16 v[30:33], v[170:173], v[162:165], v[30:33]
	ds_read_b128 v[206:209], v147 offset:4688
	ds_read_b128 v[210:213], v147 offset:6992
	ds_read_b128 v[222:225], v148 offset:41552
	ds_read_b128 v[226:229], v148 offset:43856
	s_waitcnt lgkmcnt(9)
	v_mfma_f32_16x16x32_bf16 v[34:37], v[174:177], v[150:153], v[34:37]
	v_mfma_f32_16x16x32_bf16 v[38:41], v[174:177], v[154:157], v[38:41]
	v_mfma_f32_16x16x32_bf16 v[2:5], v[174:177], v[158:161], v[2:5]
	v_mfma_f32_16x16x32_bf16 v[6:9], v[174:177], v[162:165], v[6:9]
	s_waitcnt lgkmcnt(8)
	v_mfma_f32_16x16x32_bf16 v[42:45], v[178:181], v[150:153], v[42:45]
	v_mfma_f32_16x16x32_bf16 v[46:49], v[178:181], v[154:157], v[46:49]
	s_waitcnt vmcnt(6)
	ds_write_b128 v144, v[98:101] offset:18448
	ds_write_b128 v144, v[102:105] offset:55312
	v_mfma_f32_16x16x32_bf16 v[10:13], v[178:181], v[158:161], v[10:13]
	v_mfma_f32_16x16x32_bf16 v[14:17], v[178:181], v[162:165], v[14:17]
	s_waitcnt lgkmcnt(8)
	v_mfma_f32_16x16x32_bf16 v[50:53], v[214:217], v[198:201], v[50:53]
	s_waitcnt lgkmcnt(7)
	v_mfma_f32_16x16x32_bf16 v[54:57], v[214:217], v[202:205], v[54:57]
	s_waitcnt vmcnt(4)
	ds_write_b128 v144, v[106:109] offset:23056
	ds_write_b128 v144, v[110:113] offset:59920
	s_waitcnt lgkmcnt(8)
	v_mfma_f32_16x16x32_bf16 v[58:61], v[218:221], v[198:201], v[58:61]
	v_mfma_f32_16x16x32_bf16 v[62:65], v[218:221], v[202:205], v[62:65]
	s_waitcnt lgkmcnt(7)
	v_mfma_f32_16x16x32_bf16 v[18:21], v[214:217], v[206:209], v[18:21]
	v_mfma_f32_16x16x32_bf16 v[26:29], v[218:221], v[206:209], v[26:29]
	s_waitcnt vmcnt(2)
	ds_write_b128 v144, v[114:117] offset:27664
	ds_write_b128 v144, v[118:121] offset:64528
	s_waitcnt lgkmcnt(8)
	v_mfma_f32_16x16x32_bf16 v[22:25], v[214:217], v[210:213], v[22:25]
	v_mfma_f32_16x16x32_bf16 v[30:33], v[218:221], v[210:213], v[30:33]
	s_waitcnt lgkmcnt(7)
	v_mfma_f32_16x16x32_bf16 v[34:37], v[222:225], v[198:201], v[34:37]
	v_mfma_f32_16x16x32_bf16 v[38:41], v[222:225], v[202:205], v[38:41]
	s_waitcnt vmcnt(0)
	ds_write_b128 v144, v[122:125] offset:32272
	ds_write_b128 v145, v[126:129] offset:32256
	v_mfma_f32_16x16x32_bf16 v[2:5], v[222:225], v[206:209], v[2:5]
	v_mfma_f32_16x16x32_bf16 v[6:9], v[222:225], v[210:213], v[6:9]
	s_waitcnt lgkmcnt(8)
	v_mfma_f32_16x16x32_bf16 v[42:45], v[226:229], v[198:201], v[42:45]
	v_mfma_f32_16x16x32_bf16 v[46:49], v[226:229], v[202:205], v[46:49]
	v_mfma_f32_16x16x32_bf16 v[10:13], v[226:229], v[206:209], v[10:13]
	v_mfma_f32_16x16x32_bf16 v[14:17], v[226:229], v[210:213], v[14:17]
	s_waitcnt lgkmcnt(0)
	s_barrier
; #define MFMA(a, b, c) __builtin_amdgcn_mfma_f32_32x32x16_bf16((a), (b), (c), 0, 0, 0)
; template <bool SWAP, class Epi>
; DI void gemm_tile(const u16* __restrict__ A, int lda, const u16* __restrict__ Bt, int ldb, int K, int m0, int n0, char* smem, Epi&& epi) {
;     ...
;   auto compute = [&](int buf) __attribute__((always_inline)) {
;     bf16x8 af[2][2], bfr[2][2];
;     af[0][0] = *(const bf16x8*)(Asb + buf * 128 * 72);
;     af[0][1] = *(const bf16x8*)(Asb + buf * 128 * 72 + 32 * 72);
;     bfr[0][0] = *(const bf16x8*)(Bsb + buf * 128 * 72);
;     bfr[0][1] = *(const bf16x8*)(Bsb + buf * 128 * 72 + 32 * 72);
; #pragma unroll
;     for (int ks = 0; ks < 4; ++ks) {
;       const int c = ks & 1, n = c ^ 1;
;       if (ks < 3) {
;         af[n][0] = *(const bf16x8*)(Asb + buf * 128 * 72 + (ks + 1) * 16);
;         af[n][1] = *(const bf16x8*)(Asb + buf * 128 * 72 + 32 * 72 + (ks + 1) * 16);
;         bfr[n][0] = *(const bf16x8*)(Bsb + buf * 128 * 72 + (ks + 1) * 16);
;         bfr[n][1] = *(const bf16x8*)(Bsb + buf * 128 * 72 + 32 * 72 + (ks + 1) * 16);
;       }
;       __builtin_amdgcn_sched_barrier(0);
; #pragma unroll
;       for (int mi = 0; mi < 2; ++mi)
; #pragma unroll
;         for (int ni = 0; ni < 2; ++ni) {
;           if (SWAP) acc[mi][ni] = MFMA(bfr[c][ni], af[c][mi], acc[mi][ni]);
;           else acc[mi][ni] = MFMA(af[c][mi], bfr[c][ni], acc[mi][ni]);
;         }
;       __builtin_amdgcn_sched_barrier(0);
;     }
;   };
;   for (int kt = 0; kt < KT; kt += 2) {
;     if (kt + 2 < KT) {
;       const int k0 = (kt + 2) << 6;
; #pragma unroll
;       for (int i = 0; i < 4; ++i) { ra0[i] = *(const u32x4*)(ag + (size_t)i * 32 * lda + k0); rb0[i] = *(const u32x4*)(bg + (size_t)i * 32 * ldb + k0); }
;     }
;     compute(0);
; #pragma unroll
;     for (int i = 0; i < 4; ++i) { *(u32x4*)(asw + 128 * 72 + 32 * i * 72) = ra1[i]; *(u32x4*)(bsw + 128 * 72 + 32 * i * 72) = rb1[i]; }
;     __syncthreads();
;     if (kt + 3 < KT) {
;       const int k0 = (kt + 3) << 6;
; #pragma unroll
;       for (int i = 0; i < 4; ++i) { ra1[i] = *(const u32x4*)(ag + (size_t)i * 32 * lda + k0); rb1[i] = *(const u32x4*)(bg + (size_t)i * 32 * ldb + k0); }
;     }
;     compute(1);
;     if (kt + 2 < KT) {
; #pragma unroll
;       for (int i = 0; i < 4; ++i) { *(u32x4*)(asw + 32 * i * 72) = ra0[i]; *(u32x4*)(bsw + 32 * i * 72) = rb0[i]; }
;     }
;     __syncthreads();
;   }
	ds_read_b128 v[166:169], v148 offset:55312
	ds_read_b128 v[150:153], v147 offset:18448
	ds_read_b128 v[154:157], v147 offset:20752
	ds_read_b128 v[170:173], v148 offset:57616
	ds_read_b128 v[158:161], v147 offset:23056
	ds_read_b128 v[162:165], v147 offset:25360
	ds_read_b128 v[174:177], v148 offset:59920
	ds_read_b128 v[178:181], v148 offset:62224
	s_waitcnt lgkmcnt(6)
	v_mfma_f32_16x16x32_bf16 v[50:53], v[166:169], v[150:153], v[50:53]
	s_waitcnt lgkmcnt(5)
	v_mfma_f32_16x16x32_bf16 v[54:57], v[166:169], v[154:157], v[54:57]
	s_waitcnt lgkmcnt(4)
	v_mfma_f32_16x16x32_bf16 v[58:61], v[170:173], v[150:153], v[58:61]
	v_mfma_f32_16x16x32_bf16 v[62:65], v[170:173], v[154:157], v[62:65]
	ds_read_b128 v[214:217], v148 offset:55376
	ds_read_b128 v[198:201], v147 offset:18512
	ds_read_b128 v[202:205], v147 offset:20816
	ds_read_b128 v[218:221], v148 offset:57680
	s_waitcnt lgkmcnt(7)
	v_mfma_f32_16x16x32_bf16 v[18:21], v[166:169], v[158:161], v[18:21]
	v_mfma_f32_16x16x32_bf16 v[26:29], v[170:173], v[158:161], v[26:29]
	s_waitcnt lgkmcnt(6)
	v_mfma_f32_16x16x32_bf16 v[22:25], v[166:169], v[162:165], v[22:25]
	v_mfma_f32_16x16x32_bf16 v[30:33], v[170:173], v[162:165], v[30:33]
	ds_read_b128 v[206:209], v147 offset:23120
	ds_read_b128 v[210:213], v147 offset:25424
	ds_read_b128 v[222:225], v148 offset:59984
	ds_read_b128 v[226:229], v148 offset:62288
	s_waitcnt lgkmcnt(9)
	v_mfma_f32_16x16x32_bf16 v[34:37], v[174:177], v[150:153], v[34:37]
	v_mfma_f32_16x16x32_bf16 v[38:41], v[174:177], v[154:157], v[38:41]
	v_mfma_f32_16x16x32_bf16 v[2:5], v[174:177], v[158:161], v[2:5]
	v_mfma_f32_16x16x32_bf16 v[6:9], v[174:177], v[162:165], v[6:9]
	s_waitcnt lgkmcnt(8)
	v_mfma_f32_16x16x32_bf16 v[42:45], v[178:181], v[150:153], v[42:45]
	v_mfma_f32_16x16x32_bf16 v[46:49], v[178:181], v[154:157], v[46:49]
	v_mfma_f32_16x16x32_bf16 v[10:13], v[178:181], v[158:161], v[10:13]
	v_mfma_f32_16x16x32_bf16 v[14:17], v[178:181], v[162:165], v[14:17]
	s_waitcnt lgkmcnt(6)
	v_mfma_f32_16x16x32_bf16 v[50:53], v[214:217], v[198:201], v[50:53]
	s_waitcnt lgkmcnt(5)
	v_mfma_f32_16x16x32_bf16 v[54:57], v[214:217], v[202:205], v[54:57]
	s_waitcnt lgkmcnt(4)
	v_mfma_f32_16x16x32_bf16 v[58:61], v[218:221], v[198:201], v[58:61]
	v_mfma_f32_16x16x32_bf16 v[62:65], v[218:221], v[202:205], v[62:65]
	s_waitcnt lgkmcnt(3)
	v_mfma_f32_16x16x32_bf16 v[18:21], v[214:217], v[206:209], v[18:21]
	v_mfma_f32_16x16x32_bf16 v[26:29], v[218:221], v[206:209], v[26:29]
	s_waitcnt lgkmcnt(2)
	v_mfma_f32_16x16x32_bf16 v[22:25], v[214:217], v[210:213], v[22:25]
	v_mfma_f32_16x16x32_bf16 v[30:33], v[218:221], v[210:213], v[30:33]
	s_waitcnt lgkmcnt(1)
	v_mfma_f32_16x16x32_bf16 v[34:37], v[222:225], v[198:201], v[34:37]
	v_mfma_f32_16x16x32_bf16 v[38:41], v[222:225], v[202:205], v[38:41]
	v_mfma_f32_16x16x32_bf16 v[2:5], v[222:225], v[206:209], v[2:5]
	v_mfma_f32_16x16x32_bf16 v[6:9], v[222:225], v[210:213], v[6:9]
	s_waitcnt lgkmcnt(0)
	v_mfma_f32_16x16x32_bf16 v[42:45], v[226:229], v[198:201], v[42:45]
	v_mfma_f32_16x16x32_bf16 v[46:49], v[226:229], v[202:205], v[46:49]
	v_mfma_f32_16x16x32_bf16 v[10:13], v[226:229], v[206:209], v[10:13]
	v_mfma_f32_16x16x32_bf16 v[14:17], v[226:229], v[210:213], v[14:17]
	s_nop 7
	s_nop 7
	v_permlane16_swap_b32_e32 v50, v54
	v_permlane16_swap_b32_e32 v51, v55
	v_permlane16_swap_b32_e32 v52, v56
	v_permlane16_swap_b32_e32 v53, v57
	v_permlane16_swap_b32_e32 v58, v62
	v_permlane16_swap_b32_e32 v59, v63
	v_permlane16_swap_b32_e32 v60, v64
	v_permlane16_swap_b32_e32 v61, v65
	v_permlane16_swap_b32_e32 v34, v38
	v_permlane16_swap_b32_e32 v35, v39
	v_permlane16_swap_b32_e32 v36, v40
	v_permlane16_swap_b32_e32 v37, v41
	v_permlane16_swap_b32_e32 v42, v46
	v_permlane16_swap_b32_e32 v43, v47
	v_permlane16_swap_b32_e32 v44, v48
	v_permlane16_swap_b32_e32 v45, v49
	v_permlane16_swap_b32_e32 v18, v22
	v_permlane16_swap_b32_e32 v19, v23
	v_permlane16_swap_b32_e32 v20, v24
	v_permlane16_swap_b32_e32 v21, v25
	v_permlane16_swap_b32_e32 v26, v30
	v_permlane16_swap_b32_e32 v27, v31
	v_permlane16_swap_b32_e32 v28, v32
	v_permlane16_swap_b32_e32 v29, v33
	v_permlane16_swap_b32_e32 v2, v6
	v_permlane16_swap_b32_e32 v3, v7
	v_permlane16_swap_b32_e32 v4, v8
	v_permlane16_swap_b32_e32 v5, v9
	v_permlane16_swap_b32_e32 v10, v14
	v_permlane16_swap_b32_e32 v11, v15
	v_permlane16_swap_b32_e32 v12, v16
	v_permlane16_swap_b32_e32 v13, v17
	s_waitcnt lgkmcnt(0)
	s_barrier
	s_branch .LBB0_745

; template <bool SWAP, class Epi>
; DI void gemm_tile(const u16* __restrict__ A, int lda, const u16* __restrict__ Bt, int ldb, int K, int m0, int n0, char* smem, Epi&& epi) {
;   u16* As = (u16*)(smem + 16);
;   u16* Bs = As + 2 * 128 * 72;
;   const int tid = threadIdx.x, lane = tid & 63, w = tid >> 6, wm = w >> 1, wn = w & 1;
;   const int r = lane & 31, hi = lane >> 5;
;   f32x16 acc[2][2];
; #pragma unroll
;   for (int a = 0; a < 2; ++a)
; #pragma unroll
;     for (int b = 0; b < 2; ++b)
; #pragma unroll
;       for (int i = 0; i < 16; ++i) acc[a][b][i] = 0.f;
;   const int srow = tid >> 3, skc = tid & 7;
;   const u16* ag = A + (size_t)(m0 + srow) * lda + skc * 8;
;   const u16* bg = Bt + (size_t)(n0 + srow) * ldb + skc * 8;
;   u16* asw = As + srow * 72 + skc * 8;
;   u16* bsw = Bs + srow * 72 + skc * 8;
;   u32x4 ra0[4], rb0[4], ra1[4], rb1[4];
; #pragma unroll
;   for (int i = 0; i < 4; ++i) { ra0[i] = *(const u32x4*)(ag + (size_t)i * 32 * lda); rb0[i] = *(const u32x4*)(bg + (size_t)i * 32 * ldb); }
; #pragma unroll
;   for (int i = 0; i < 4; ++i) { ra1[i] = *(const u32x4*)(ag + (size_t)i * 32 * lda + 64); rb1[i] = *(const u32x4*)(bg + (size_t)i * 32 * ldb + 64); }
;   __syncthreads();
; #pragma unroll
;   for (int i = 0; i < 4; ++i) { *(u32x4*)(asw + 32 * i * 72) = ra0[i]; *(u32x4*)(bsw + 32 * i * 72) = rb0[i]; }
;   __syncthreads();
;   const int KT = K >> 6;
;   const u16* Asb = As + (wm * 64 + r) * 72 + hi * 8;
;   const u16* Bsb = Bs + (wn * 64 + r) * 72 + hi * 8;
; DI void phase7(const Params& p, char* smem) {
;   const u16* H2 = (const u16*)(p.ws + WS_H); const u16* W = (const u16*)(p.ws + WS_WQT); u16* PQ = (u16*)(p.ws + WS_P);
;   for (int it = blockIdx.x; it < 64 * 16; it += gridDim.x) {
;     const int tn = it / 64, tm = it % 64;
;     gemm_tile<true>(H2, D_, W, D_, D_, tm * 128, tn * 128, smem, [&](f32x16 (&acc)[2][2], int mb, int nb, int r, int hi) __attribute__((always_inline)) {
.Lprio_p7:
	s_waitcnt lgkmcnt(0)
	v_lshlrev_b32_e32 v2, 4, v0
	v_and_b32_e32 v130, 0x70, v2
	v_mov_b32_e32 v131, 0
	v_lshl_add_u64 v[2:3], s[82:83], 0, v[130:131]
	s_mov_b64 s[4:5], 0x6538000
	v_lshrrev_b32_e32 v1, 3, v0
	s_waitcnt vmcnt(9)
	v_lshl_add_u64 v[132:133], v[2:3], 0, s[4:5]
	s_mov_b64 s[4:5], 0x1cb8000
	v_lshl_add_u64 v[134:135], v[2:3], 0, s[4:5]
	v_mul_u32_u24_e32 v2, 0x48, v1
	v_and_b32_e32 v4, 31, v0
	v_lshlrev_b32_e32 v2, 1, v2
	v_lshrrev_b32_e32 v3, 1, v0
	s_waitcnt vmcnt(6)
	v_add3_u32 v144, 0, v2, v130
	v_bfe_u32 v2, v0, 5, 1
	v_and_or_b32 v146, v3, 64, v4
	v_mul_u32_u24_e32 v3, 0x90, v146
	v_lshlrev_b32_e32 v4, 4, v2
	v_add3_u32 v147, 0, v3, v4
	v_and_b32_e32 v3, 0x5f, v0
	s_load_dword s10, s[0:1], 0xc0
	v_mul_u32_u24_e32 v3, 0x90, v3
	s_waitcnt vmcnt(5)
	v_add3_u32 v148, 0, v3, v4
	v_and_b32_e32 v3, 64, v0
	s_add_u32 s2, s82, 0x8538000
	v_lshl_or_b32 v149, v2, 2, v3
	v_and_b32_e32 v2, 7, v0
	s_addc_u32 s3, s83, 0
	v_add_u32_e32 v145, 0x9010, v144
	v_lshlrev_b32_e32 v130, 4, v2
	s_mov_b32 s11, 0x20000
	s_mov_b32 s13, 0x40000
	s_mov_b32 s14, 0x60000
	s_mov_b64 s[4:5], 0x100
	s_mov_b32 s15, s12
	v_lshrrev_b32_e32 v198, 3, v0
	v_lshrrev_b32_e32 v199, 2, v198
	v_lshrrev_b32_e32 v200, 3, v198
	v_xor_b32_e32 v199, v199, v200
	v_and_b32_e32 v199, 1, v199
	v_and_b32_e32 v200, 1, v0
	v_lshlrev_b32_e32 v200, 5, v200
	v_sub_u32_e32 v200, 16, v200
	v_mul_lo_u32 v199, v199, v200
	v_add_u32_e32 v144, v144, v199
	v_add_u32_e32 v145, v145, v199
	v_and_b32_e32 v198, 15, v0
	v_bfe_u32 v199, v0, 4, 2
	v_lshrrev_b32_e32 v200, 2, v198
	v_lshrrev_b32_e32 v201, 3, v198
	v_xor_b32_e32 v200, v200, v201
	v_and_b32_e32 v200, 1, v200
	v_xor_b32_e32 v199, v199, v200
	v_lshlrev_b32_e32 v199, 4, v199
	v_bfe_u32 v200, v0, 7, 1
	v_lshl_or_b32 v200, v200, 6, v198
	v_mul_u32_u24_e32 v200, 0x90, v200
	v_add_u32_e32 v147, v200, v199
	v_and_b32_e32 v201, 3, v198
	v_and_b32_e32 v202, 4, v198
	v_lshlrev_b32_e32 v202, 1, v202
	v_and_b32_e32 v203, 8, v198
	v_lshrrev_b32_e32 v203, 1, v203
	v_or3_b32 v198, v201, v202, v203
	v_bfe_u32 v200, v0, 6, 1
	v_lshl_or_b32 v200, v200, 6, v198
	v_mul_u32_u24_e32 v200, 0x90, v200
	v_add_u32_e32 v148, v200, v199
	s_branch .LBB0_953

; #define MFMA(a, b, c) __builtin_amdgcn_mfma_f32_32x32x16_bf16((a), (b), (c), 0, 0, 0)
; template <bool SWAP, class Epi>
; DI void gemm_tile(const u16* __restrict__ A, int lda, const u16* __restrict__ Bt, int ldb, int K, int m0, int n0, char* smem, Epi&& epi) {
;     ...
;   auto compute = [&](int buf) __attribute__((always_inline)) {
;     bf16x8 af[2][2], bfr[2][2];
;     af[0][0] = *(const bf16x8*)(Asb + buf * 128 * 72);
;     af[0][1] = *(const bf16x8*)(Asb + buf * 128 * 72 + 32 * 72);
;     bfr[0][0] = *(const bf16x8*)(Bsb + buf * 128 * 72);
;     bfr[0][1] = *(const bf16x8*)(Bsb + buf * 128 * 72 + 32 * 72);
; #pragma unroll
;     for (int ks = 0; ks < 4; ++ks) {
;       const int c = ks & 1, n = c ^ 1;
;       if (ks < 3) {
;         af[n][0] = *(const bf16x8*)(Asb + buf * 128 * 72 + (ks + 1) * 16);
;         af[n][1] = *(const bf16x8*)(Asb + buf * 128 * 72 + 32 * 72 + (ks + 1) * 16);
;         bfr[n][0] = *(const bf16x8*)(Bsb + buf * 128 * 72 + (ks + 1) * 16);
;         bfr[n][1] = *(const bf16x8*)(Bsb + buf * 128 * 72 + 32 * 72 + (ks + 1) * 16);
;       }
;       __builtin_amdgcn_sched_barrier(0);
; #pragma unroll
;       for (int mi = 0; mi < 2; ++mi)
; #pragma unroll
;         for (int ni = 0; ni < 2; ++ni) {
;           if (SWAP) acc[mi][ni] = MFMA(bfr[c][ni], af[c][mi], acc[mi][ni]);
;           else acc[mi][ni] = MFMA(af[c][mi], bfr[c][ni], acc[mi][ni]);
;         }
;       __builtin_amdgcn_sched_barrier(0);
;     }
;   };
;   for (int kt = 0; kt < KT; kt += 2) {
;     if (kt + 2 < KT) {
;       const int k0 = (kt + 2) << 6;
; #pragma unroll
;       for (int i = 0; i < 4; ++i) { ra0[i] = *(const u32x4*)(ag + (size_t)i * 32 * lda + k0); rb0[i] = *(const u32x4*)(bg + (size_t)i * 32 * ldb + k0); }
;     }
;     compute(0);
; #pragma unroll
;     for (int i = 0; i < 4; ++i) { *(u32x4*)(asw + 128 * 72 + 32 * i * 72) = ra1[i]; *(u32x4*)(bsw + 128 * 72 + 32 * i * 72) = rb1[i]; }
;     __syncthreads();
;     if (kt + 3 < KT) {
;       const int k0 = (kt + 3) << 6;
; #pragma unroll
;       for (int i = 0; i < 4; ++i) { ra1[i] = *(const u32x4*)(ag + (size_t)i * 32 * lda + k0); rb1[i] = *(const u32x4*)(bg + (size_t)i * 32 * ldb + k0); }
;     }
;     compute(1);
;     if (kt + 2 < KT) {
; #pragma unroll
;       for (int i = 0; i < 4; ++i) { *(u32x4*)(asw + 32 * i * 72) = ra0[i]; *(u32x4*)(bsw + 32 * i * 72) = rb0[i]; }
;     }
;     __syncthreads();
;   }
.LBB0_955:
	global_load_dwordx4 v[66:69], v194, s[100:101] offset:256
	global_load_dwordx4 v[70:73], v190, s[98:99] offset:256
	global_load_dwordx4 v[74:77], v195, s[100:101] offset:256
	global_load_dwordx4 v[78:81], v191, s[98:99] offset:256
	global_load_dwordx4 v[82:85], v196, s[100:101] offset:256
	global_load_dwordx4 v[86:89], v192, s[98:99] offset:256
	global_load_dwordx4 v[90:93], v197, s[100:101] offset:256
	global_load_dwordx4 v[94:97], v193, s[98:99] offset:256
	ds_read_b128 v[166:169], v148 offset:36880
	ds_read_b128 v[150:153], v147 offset:16
	ds_read_b128 v[154:157], v147 offset:2320
	ds_read_b128 v[170:173], v148 offset:39184
	ds_read_b128 v[158:161], v147 offset:4624
	ds_read_b128 v[162:165], v147 offset:6928
	ds_read_b128 v[174:177], v148 offset:41488
	ds_read_b128 v[178:181], v148 offset:43792
	s_waitcnt lgkmcnt(6)
	v_mfma_f32_16x16x32_bf16 v[50:53], v[166:169], v[150:153], v[50:53]
	s_waitcnt lgkmcnt(5)
	v_mfma_f32_16x16x32_bf16 v[54:57], v[166:169], v[154:157], v[54:57]
	s_waitcnt lgkmcnt(4)
	v_mfma_f32_16x16x32_bf16 v[58:61], v[170:173], v[150:153], v[58:61]
	v_mfma_f32_16x16x32_bf16 v[62:65], v[170:173], v[154:157], v[62:65]
	ds_read_b128 v[214:217], v148 offset:36944
	ds_read_b128 v[198:201], v147 offset:80
	ds_read_b128 v[202:205], v147 offset:2384
	ds_read_b128 v[218:221], v148 offset:39248
	s_waitcnt lgkmcnt(7)
	v_mfma_f32_16x16x32_bf16 v[18:21], v[166:169], v[158:161], v[18:21]
	v_mfma_f32_16x16x32_bf16 v[26:29], v[170:173], v[158:161], v[26:29]
	s_waitcnt lgkmcnt(6)
	v_mfma_f32_16x16x32_bf16 v[22:25], v[166:169], v[162:165], v[22:25]
	v_mfma_f32_16x16x32_bf16 v[30:33], v[170:173], v[162:165], v[30:33]
	ds_read_b128 v[206:209], v147 offset:4688
	ds_read_b128 v[210:213], v147 offset:6992
	ds_read_b128 v[222:225], v148 offset:41552
	ds_read_b128 v[226:229], v148 offset:43856
	s_waitcnt lgkmcnt(9)
	v_mfma_f32_16x16x32_bf16 v[34:37], v[174:177], v[150:153], v[34:37]
	v_mfma_f32_16x16x32_bf16 v[38:41], v[174:177], v[154:157], v[38:41]
	v_mfma_f32_16x16x32_bf16 v[2:5], v[174:177], v[158:161], v[2:5]
	v_mfma_f32_16x16x32_bf16 v[6:9], v[174:177], v[162:165], v[6:9]
	s_waitcnt lgkmcnt(8)
	v_mfma_f32_16x16x32_bf16 v[42:45], v[178:181], v[150:153], v[42:45]
	v_mfma_f32_16x16x32_bf16 v[46:49], v[178:181], v[154:157], v[46:49]
	s_waitcnt vmcnt(14)
	ds_write_b128 v144, v[98:101] offset:18448
	ds_write_b128 v144, v[102:105] offset:55312
	v_mfma_f32_16x16x32_bf16 v[10:13], v[178:181], v[158:161], v[10:13]
	v_mfma_f32_16x16x32_bf16 v[14:17], v[178:181], v[162:165], v[14:17]
	s_waitcnt lgkmcnt(8)
	v_mfma_f32_16x16x32_bf16 v[50:53], v[214:217], v[198:201], v[50:53]
	s_waitcnt lgkmcnt(7)
	v_mfma_f32_16x16x32_bf16 v[54:57], v[214:217], v[202:205], v[54:57]
	s_waitcnt vmcnt(12)
	ds_write_b128 v144, v[106:109] offset:23056
	ds_write_b128 v144, v[110:113] offset:59920
	s_waitcnt lgkmcnt(8)
	v_mfma_f32_16x16x32_bf16 v[58:61], v[218:221], v[198:201], v[58:61]
	v_mfma_f32_16x16x32_bf16 v[62:65], v[218:221], v[202:205], v[62:65]
	s_waitcnt lgkmcnt(7)
	v_mfma_f32_16x16x32_bf16 v[18:21], v[214:217], v[206:209], v[18:21]
	v_mfma_f32_16x16x32_bf16 v[26:29], v[218:221], v[206:209], v[26:29]
	s_waitcnt vmcnt(10)
	ds_write_b128 v144, v[114:117] offset:27664
	ds_write_b128 v144, v[118:121] offset:64528
	s_waitcnt lgkmcnt(8)
	v_mfma_f32_16x16x32_bf16 v[22:25], v[214:217], v[210:213], v[22:25]
	v_mfma_f32_16x16x32_bf16 v[30:33], v[218:221], v[210:213], v[30:33]
	s_waitcnt lgkmcnt(7)
	v_mfma_f32_16x16x32_bf16 v[34:37], v[222:225], v[198:201], v[34:37]
	v_mfma_f32_16x16x32_bf16 v[38:41], v[222:225], v[202:205], v[38:41]
	s_waitcnt vmcnt(8)
	ds_write_b128 v144, v[122:125] offset:32272
	ds_write_b128 v145, v[126:129] offset:32256
	v_mfma_f32_16x16x32_bf16 v[2:5], v[222:225], v[206:209], v[2:5]
	v_mfma_f32_16x16x32_bf16 v[6:9], v[222:225], v[210:213], v[6:9]
	s_waitcnt lgkmcnt(8)
	v_mfma_f32_16x16x32_bf16 v[42:45], v[226:229], v[198:201], v[42:45]
	v_mfma_f32_16x16x32_bf16 v[46:49], v[226:229], v[202:205], v[46:49]
	v_mfma_f32_16x16x32_bf16 v[10:13], v[226:229], v[206:209], v[10:13]
	v_mfma_f32_16x16x32_bf16 v[14:17], v[226:229], v[210:213], v[14:17]
	s_waitcnt lgkmcnt(0)
	s_barrier
	global_load_dwordx4 v[98:101], v194, s[100:101] offset:384
	global_load_dwordx4 v[102:105], v190, s[98:99] offset:384
	global_load_dwordx4 v[106:109], v195, s[100:101] offset:384
	global_load_dwordx4 v[110:113], v191, s[98:99] offset:384
	global_load_dwordx4 v[114:117], v196, s[100:101] offset:384
	global_load_dwordx4 v[118:121], v192, s[98:99] offset:384
	global_load_dwordx4 v[122:125], v197, s[100:101] offset:384
	global_load_dwordx4 v[126:129], v193, s[98:99] offset:384
	ds_read_b128 v[166:169], v148 offset:55312
	ds_read_b128 v[150:153], v147 offset:18448
	ds_read_b128 v[154:157], v147 offset:20752
	ds_read_b128 v[170:173], v148 offset:57616
	ds_read_b128 v[158:161], v147 offset:23056
	ds_read_b128 v[162:165], v147 offset:25360
	ds_read_b128 v[174:177], v148 offset:59920
	ds_read_b128 v[178:181], v148 offset:62224
	s_waitcnt lgkmcnt(6)
	v_mfma_f32_16x16x32_bf16 v[50:53], v[166:169], v[150:153], v[50:53]
	s_waitcnt lgkmcnt(5)
	v_mfma_f32_16x16x32_bf16 v[54:57], v[166:169], v[154:157], v[54:57]
	s_waitcnt lgkmcnt(4)
	v_mfma_f32_16x16x32_bf16 v[58:61], v[170:173], v[150:153], v[58:61]
	v_mfma_f32_16x16x32_bf16 v[62:65], v[170:173], v[154:157], v[62:65]
	ds_read_b128 v[214:217], v148 offset:55376
	ds_read_b128 v[198:201], v147 offset:18512
	ds_read_b128 v[202:205], v147 offset:20816
	ds_read_b128 v[218:221], v148 offset:57680
	s_waitcnt lgkmcnt(7)
	v_mfma_f32_16x16x32_bf16 v[18:21], v[166:169], v[158:161], v[18:21]
	v_mfma_f32_16x16x32_bf16 v[26:29], v[170:173], v[158:161], v[26:29]
	s_waitcnt lgkmcnt(6)
; #define MFMA(a, b, c) __builtin_amdgcn_mfma_f32_32x32x16_bf16((a), (b), (c), 0, 0, 0)
; template <bool SWAP, class Epi>
; DI void gemm_tile(const u16* __restrict__ A, int lda, const u16* __restrict__ Bt, int ldb, int K, int m0, int n0, char* smem, Epi&& epi) {
;     ...
;   auto compute = [&](int buf) __attribute__((always_inline)) {
;     bf16x8 af[2][2], bfr[2][2];
;     af[0][0] = *(const bf16x8*)(Asb + buf * 128 * 72);
;     af[0][1] = *(const bf16x8*)(Asb + buf * 128 * 72 + 32 * 72);
;     bfr[0][0] = *(const bf16x8*)(Bsb + buf * 128 * 72);
;     bfr[0][1] = *(const bf16x8*)(Bsb + buf * 128 * 72 + 32 * 72);
; #pragma unroll
;     for (int ks = 0; ks < 4; ++ks) {
;       const int c = ks & 1, n = c ^ 1;
;       if (ks < 3) {
;         af[n][0] = *(const bf16x8*)(Asb + buf * 128 * 72 + (ks + 1) * 16);
;         af[n][1] = *(const bf16x8*)(Asb + buf * 128 * 72 + 32 * 72 + (ks + 1) * 16);
;         bfr[n][0] = *(const bf16x8*)(Bsb + buf * 128 * 72 + (ks + 1) * 16);
;         bfr[n][1] = *(const bf16x8*)(Bsb + buf * 128 * 72 + 32 * 72 + (ks + 1) * 16);
;       }
;       __builtin_amdgcn_sched_barrier(0);
; #pragma unroll
;       for (int mi = 0; mi < 2; ++mi)
; #pragma unroll
;         for (int ni = 0; ni < 2; ++ni) {
;           if (SWAP) acc[mi][ni] = MFMA(bfr[c][ni], af[c][mi], acc[mi][ni]);
;           else acc[mi][ni] = MFMA(af[c][mi], bfr[c][ni], acc[mi][ni]);
;         }
;       __builtin_amdgcn_sched_barrier(0);
;     }
;   };
;   for (int kt = 0; kt < KT; kt += 2) {
;     if (kt + 2 < KT) {
;       const int k0 = (kt + 2) << 6;
; #pragma unroll
;       for (int i = 0; i < 4; ++i) { ra0[i] = *(const u32x4*)(ag + (size_t)i * 32 * lda + k0); rb0[i] = *(const u32x4*)(bg + (size_t)i * 32 * ldb + k0); }
;     }
;     compute(0);
; #pragma unroll
;     for (int i = 0; i < 4; ++i) { *(u32x4*)(asw + 128 * 72 + 32 * i * 72) = ra1[i]; *(u32x4*)(bsw + 128 * 72 + 32 * i * 72) = rb1[i]; }
;     __syncthreads();
;     if (kt + 3 < KT) {
;       const int k0 = (kt + 3) << 6;
; #pragma unroll
;       for (int i = 0; i < 4; ++i) { ra1[i] = *(const u32x4*)(ag + (size_t)i * 32 * lda + k0); rb1[i] = *(const u32x4*)(bg + (size_t)i * 32 * ldb + k0); }
;     }
;     compute(1);
;     if (kt + 2 < KT) {
; #pragma unroll
;       for (int i = 0; i < 4; ++i) { *(u32x4*)(asw + 32 * i * 72) = ra0[i]; *(u32x4*)(bsw + 32 * i * 72) = rb0[i]; }
;     }
;     __syncthreads();
;   }
	v_mfma_f32_16x16x32_bf16 v[22:25], v[166:169], v[162:165], v[22:25]
	v_mfma_f32_16x16x32_bf16 v[30:33], v[170:173], v[162:165], v[30:33]
	ds_read_b128 v[206:209], v147 offset:23120
	ds_read_b128 v[210:213], v147 offset:25424
	ds_read_b128 v[222:225], v148 offset:59984
	ds_read_b128 v[226:229], v148 offset:62288
	s_waitcnt lgkmcnt(9)
	v_mfma_f32_16x16x32_bf16 v[34:37], v[174:177], v[150:153], v[34:37]
	v_mfma_f32_16x16x32_bf16 v[38:41], v[174:177], v[154:157], v[38:41]
	v_mfma_f32_16x16x32_bf16 v[2:5], v[174:177], v[158:161], v[2:5]
	v_mfma_f32_16x16x32_bf16 v[6:9], v[174:177], v[162:165], v[6:9]
	s_waitcnt lgkmcnt(8)
	v_mfma_f32_16x16x32_bf16 v[42:45], v[178:181], v[150:153], v[42:45]
	v_mfma_f32_16x16x32_bf16 v[46:49], v[178:181], v[154:157], v[46:49]
	s_waitcnt vmcnt(14)
	ds_write_b128 v144, v[66:69] offset:16
	ds_write_b128 v144, v[70:73] offset:36880
	v_mfma_f32_16x16x32_bf16 v[10:13], v[178:181], v[158:161], v[10:13]
	v_mfma_f32_16x16x32_bf16 v[14:17], v[178:181], v[162:165], v[14:17]
	s_waitcnt lgkmcnt(8)
	v_mfma_f32_16x16x32_bf16 v[50:53], v[214:217], v[198:201], v[50:53]
	s_waitcnt lgkmcnt(7)
	v_mfma_f32_16x16x32_bf16 v[54:57], v[214:217], v[202:205], v[54:57]
	s_waitcnt vmcnt(12)
	ds_write_b128 v144, v[74:77] offset:4624
	ds_write_b128 v144, v[78:81] offset:41488
	s_waitcnt lgkmcnt(8)
	v_mfma_f32_16x16x32_bf16 v[58:61], v[218:221], v[198:201], v[58:61]
	v_mfma_f32_16x16x32_bf16 v[62:65], v[218:221], v[202:205], v[62:65]
	s_waitcnt lgkmcnt(7)
	v_mfma_f32_16x16x32_bf16 v[18:21], v[214:217], v[206:209], v[18:21]
	v_mfma_f32_16x16x32_bf16 v[26:29], v[218:221], v[206:209], v[26:29]
	s_waitcnt vmcnt(10)
	ds_write_b128 v144, v[82:85] offset:9232
	ds_write_b128 v144, v[86:89] offset:46096
	s_waitcnt lgkmcnt(8)
	v_mfma_f32_16x16x32_bf16 v[22:25], v[214:217], v[210:213], v[22:25]
	v_mfma_f32_16x16x32_bf16 v[30:33], v[218:221], v[210:213], v[30:33]
	s_waitcnt lgkmcnt(7)
	v_mfma_f32_16x16x32_bf16 v[34:37], v[222:225], v[198:201], v[34:37]
	v_mfma_f32_16x16x32_bf16 v[38:41], v[222:225], v[202:205], v[38:41]
	s_waitcnt vmcnt(8)
	ds_write_b128 v144, v[90:93] offset:13840
	ds_write_b128 v144, v[94:97] offset:50704
	v_mfma_f32_16x16x32_bf16 v[2:5], v[222:225], v[206:209], v[2:5]
	v_mfma_f32_16x16x32_bf16 v[6:9], v[222:225], v[210:213], v[6:9]
	s_waitcnt lgkmcnt(8)
	v_mfma_f32_16x16x32_bf16 v[42:45], v[226:229], v[198:201], v[42:45]
	v_mfma_f32_16x16x32_bf16 v[46:49], v[226:229], v[202:205], v[46:49]
	v_mfma_f32_16x16x32_bf16 v[10:13], v[226:229], v[206:209], v[10:13]
	v_mfma_f32_16x16x32_bf16 v[14:17], v[226:229], v[210:213], v[14:17]
	s_add_i32 s18, s18, 2
	s_add_u32 s98, s98, 256
	s_addc_u32 s99, s99, 0
	s_add_u32 s100, s100, 256
	s_addc_u32 s101, s101, 0
	s_waitcnt lgkmcnt(0)
	s_barrier
	s_cmp_lt_u32 s18, 30
	s_cbranch_scc1 .LBB0_955
	ds_read_b128 v[166:169], v148 offset:36880
	ds_read_b128 v[150:153], v147 offset:16
	ds_read_b128 v[154:157], v147 offset:2320
	ds_read_b128 v[170:173], v148 offset:39184
	ds_read_b128 v[158:161], v147 offset:4624
	ds_read_b128 v[162:165], v147 offset:6928
	ds_read_b128 v[174:177], v148 offset:41488
	ds_read_b128 v[178:181], v148 offset:43792
	s_waitcnt lgkmcnt(6)
	v_mfma_f32_16x16x32_bf16 v[50:53], v[166:169], v[150:153], v[50:53]
	s_waitcnt lgkmcnt(5)
	v_mfma_f32_16x16x32_bf16 v[54:57], v[166:169], v[154:157], v[54:57]
	s_waitcnt lgkmcnt(4)
	v_mfma_f32_16x16x32_bf16 v[58:61], v[170:173], v[150:153], v[58:61]
	v_mfma_f32_16x16x32_bf16 v[62:65], v[170:173], v[154:157], v[62:65]
	ds_read_b128 v[214:217], v148 offset:36944
	ds_read_b128 v[198:201], v147 offset:80
	ds_read_b128 v[202:205], v147 offset:2384
	ds_read_b128 v[218:221], v148 offset:39248
	s_waitcnt lgkmcnt(7)
	v_mfma_f32_16x16x32_bf16 v[18:21], v[166:169], v[158:161], v[18:21]
	v_mfma_f32_16x16x32_bf16 v[26:29], v[170:173], v[158:161], v[26:29]
	s_waitcnt lgkmcnt(6)
	v_mfma_f32_16x16x32_bf16 v[22:25], v[166:169], v[162:165], v[22:25]
	v_mfma_f32_16x16x32_bf16 v[30:33], v[170:173], v[162:165], v[30:33]
	ds_read_b128 v[206:209], v147 offset:4688
	ds_read_b128 v[210:213], v147 offset:6992
	ds_read_b128 v[222:225], v148 offset:41552
	ds_read_b128 v[226:229], v148 offset:43856
	s_waitcnt lgkmcnt(9)
	v_mfma_f32_16x16x32_bf16 v[34:37], v[174:177], v[150:153], v[34:37]
	v_mfma_f32_16x16x32_bf16 v[38:41], v[174:177], v[154:157], v[38:41]
	v_mfma_f32_16x16x32_bf16 v[2:5], v[174:177], v[158:161], v[2:5]
	v_mfma_f32_16x16x32_bf16 v[6:9], v[174:177], v[162:165], v[6:9]
	s_waitcnt lgkmcnt(8)
	v_mfma_f32_16x16x32_bf16 v[42:45], v[178:181], v[150:153], v[42:45]
	v_mfma_f32_16x16x32_bf16 v[46:49], v[178:181], v[154:157], v[46:49]
	s_waitcnt vmcnt(6)
	ds_write_b128 v144, v[98:101] offset:18448
	ds_write_b128 v144, v[102:105] offset:55312
	v_mfma_f32_16x16x32_bf16 v[10:13], v[178:181], v[158:161], v[10:13]
	v_mfma_f32_16x16x32_bf16 v[14:17], v[178:181], v[162:165], v[14:17]
	s_waitcnt lgkmcnt(8)
	v_mfma_f32_16x16x32_bf16 v[50:53], v[214:217], v[198:201], v[50:53]
	s_waitcnt lgkmcnt(7)
	v_mfma_f32_16x16x32_bf16 v[54:57], v[214:217], v[202:205], v[54:57]
	s_waitcnt vmcnt(4)
	ds_write_b128 v144, v[106:109] offset:23056
	ds_write_b128 v144, v[110:113] offset:59920
	s_waitcnt lgkmcnt(8)
	v_mfma_f32_16x16x32_bf16 v[58:61], v[218:221], v[198:201], v[58:61]
	v_mfma_f32_16x16x32_bf16 v[62:65], v[218:221], v[202:205], v[62:65]
	s_waitcnt lgkmcnt(7)
	v_mfma_f32_16x16x32_bf16 v[18:21], v[214:217], v[206:209], v[18:21]
	v_mfma_f32_16x16x32_bf16 v[26:29], v[218:221], v[206:209], v[26:29]
	s_waitcnt vmcnt(2)
	ds_write_b128 v144, v[114:117] offset:27664
	ds_write_b128 v144, v[118:121] offset:64528
	s_waitcnt lgkmcnt(8)
	v_mfma_f32_16x16x32_bf16 v[22:25], v[214:217], v[210:213], v[22:25]
	v_mfma_f32_16x16x32_bf16 v[30:33], v[218:221], v[210:213], v[30:33]
	s_waitcnt lgkmcnt(7)
	v_mfma_f32_16x16x32_bf16 v[34:37], v[222:225], v[198:201], v[34:37]
	v_mfma_f32_16x16x32_bf16 v[38:41], v[222:225], v[202:205], v[38:41]
	s_waitcnt vmcnt(0)
	ds_write_b128 v144, v[122:125] offset:32272
	ds_write_b128 v145, v[126:129] offset:32256
	v_mfma_f32_16x16x32_bf16 v[2:5], v[222:225], v[206:209], v[2:5]
	v_mfma_f32_16x16x32_bf16 v[6:9], v[222:225], v[210:213], v[6:9]
	s_waitcnt lgkmcnt(8)
	v_mfma_f32_16x16x32_bf16 v[42:45], v[226:229], v[198:201], v[42:45]
	v_mfma_f32_16x16x32_bf16 v[46:49], v[226:229], v[202:205], v[46:49]
	v_mfma_f32_16x16x32_bf16 v[10:13], v[226:229], v[206:209], v[10:13]
	v_mfma_f32_16x16x32_bf16 v[14:17], v[226:229], v[210:213], v[14:17]
	s_waitcnt lgkmcnt(0)
	s_barrier
; #define MFMA(a, b, c) __builtin_amdgcn_mfma_f32_32x32x16_bf16((a), (b), (c), 0, 0, 0)
; template <bool SWAP, class Epi>
; DI void gemm_tile(const u16* __restrict__ A, int lda, const u16* __restrict__ Bt, int ldb, int K, int m0, int n0, char* smem, Epi&& epi) {
;     ...
;   auto compute = [&](int buf) __attribute__((always_inline)) {
;     bf16x8 af[2][2], bfr[2][2];
;     af[0][0] = *(const bf16x8*)(Asb + buf * 128 * 72);
;     af[0][1] = *(const bf16x8*)(Asb + buf * 128 * 72 + 32 * 72);
;     bfr[0][0] = *(const bf16x8*)(Bsb + buf * 128 * 72);
;     bfr[0][1] = *(const bf16x8*)(Bsb + buf * 128 * 72 + 32 * 72);
; #pragma unroll
;     for (int ks = 0; ks < 4; ++ks) {
;       const int c = ks & 1, n = c ^ 1;
;       if (ks < 3) {
;         af[n][0] = *(const bf16x8*)(Asb + buf * 128 * 72 + (ks + 1) * 16);
;         af[n][1] = *(const bf16x8*)(Asb + buf * 128 * 72 + 32 * 72 + (ks + 1) * 16);
;         bfr[n][0] = *(const bf16x8*)(Bsb + buf * 128 * 72 + (ks + 1) * 16);
;         bfr[n][1] = *(const bf16x8*)(Bsb + buf * 128 * 72 + 32 * 72 + (ks + 1) * 16);
;       }
;       __builtin_amdgcn_sched_barrier(0);
; #pragma unroll
;       for (int mi = 0; mi < 2; ++mi)
; #pragma unroll
;         for (int ni = 0; ni < 2; ++ni) {
;           if (SWAP) acc[mi][ni] = MFMA(bfr[c][ni], af[c][mi], acc[mi][ni]);
;           else acc[mi][ni] = MFMA(af[c][mi], bfr[c][ni], acc[mi][ni]);
;         }
;       __builtin_amdgcn_sched_barrier(0);
;     }
;   };
;   for (int kt = 0; kt < KT; kt += 2) {
;     if (kt + 2 < KT) {
;       const int k0 = (kt + 2) << 6;
; #pragma unroll
;       for (int i = 0; i < 4; ++i) { ra0[i] = *(const u32x4*)(ag + (size_t)i * 32 * lda + k0); rb0[i] = *(const u32x4*)(bg + (size_t)i * 32 * ldb + k0); }
;     }
;     compute(0);
; #pragma unroll
;     for (int i = 0; i < 4; ++i) { *(u32x4*)(asw + 128 * 72 + 32 * i * 72) = ra1[i]; *(u32x4*)(bsw + 128 * 72 + 32 * i * 72) = rb1[i]; }
;     __syncthreads();
;     if (kt + 3 < KT) {
;       const int k0 = (kt + 3) << 6;
; #pragma unroll
;       for (int i = 0; i < 4; ++i) { ra1[i] = *(const u32x4*)(ag + (size_t)i * 32 * lda + k0); rb1[i] = *(const u32x4*)(bg + (size_t)i * 32 * ldb + k0); }
;     }
;     compute(1);
;     if (kt + 2 < KT) {
; #pragma unroll
;       for (int i = 0; i < 4; ++i) { *(u32x4*)(asw + 32 * i * 72) = ra0[i]; *(u32x4*)(bsw + 32 * i * 72) = rb0[i]; }
;     }
;     __syncthreads();
;   }
	ds_read_b128 v[166:169], v148 offset:55312
	ds_read_b128 v[150:153], v147 offset:18448
	ds_read_b128 v[154:157], v147 offset:20752
	ds_read_b128 v[170:173], v148 offset:57616
	ds_read_b128 v[158:161], v147 offset:23056
	ds_read_b128 v[162:165], v147 offset:25360
	ds_read_b128 v[174:177], v148 offset:59920
	ds_read_b128 v[178:181], v148 offset:62224
	s_waitcnt lgkmcnt(6)
	v_mfma_f32_16x16x32_bf16 v[50:53], v[166:169], v[150:153], v[50:53]
	s_waitcnt lgkmcnt(5)
	v_mfma_f32_16x16x32_bf16 v[54:57], v[166:169], v[154:157], v[54:57]
	s_waitcnt lgkmcnt(4)
	v_mfma_f32_16x16x32_bf16 v[58:61], v[170:173], v[150:153], v[58:61]
	v_mfma_f32_16x16x32_bf16 v[62:65], v[170:173], v[154:157], v[62:65]
	ds_read_b128 v[214:217], v148 offset:55376
	ds_read_b128 v[198:201], v147 offset:18512
	ds_read_b128 v[202:205], v147 offset:20816
	ds_read_b128 v[218:221], v148 offset:57680
	s_waitcnt lgkmcnt(7)
	v_mfma_f32_16x16x32_bf16 v[18:21], v[166:169], v[158:161], v[18:21]
	v_mfma_f32_16x16x32_bf16 v[26:29], v[170:173], v[158:161], v[26:29]
	s_waitcnt lgkmcnt(6)
	v_mfma_f32_16x16x32_bf16 v[22:25], v[166:169], v[162:165], v[22:25]
	v_mfma_f32_16x16x32_bf16 v[30:33], v[170:173], v[162:165], v[30:33]
	ds_read_b128 v[206:209], v147 offset:23120
	ds_read_b128 v[210:213], v147 offset:25424
	ds_read_b128 v[222:225], v148 offset:59984
	ds_read_b128 v[226:229], v148 offset:62288
	s_waitcnt lgkmcnt(9)
	v_mfma_f32_16x16x32_bf16 v[34:37], v[174:177], v[150:153], v[34:37]
	v_mfma_f32_16x16x32_bf16 v[38:41], v[174:177], v[154:157], v[38:41]
	v_mfma_f32_16x16x32_bf16 v[2:5], v[174:177], v[158:161], v[2:5]
	v_mfma_f32_16x16x32_bf16 v[6:9], v[174:177], v[162:165], v[6:9]
	s_waitcnt lgkmcnt(8)
	v_mfma_f32_16x16x32_bf16 v[42:45], v[178:181], v[150:153], v[42:45]
	v_mfma_f32_16x16x32_bf16 v[46:49], v[178:181], v[154:157], v[46:49]
	v_mfma_f32_16x16x32_bf16 v[10:13], v[178:181], v[158:161], v[10:13]
	v_mfma_f32_16x16x32_bf16 v[14:17], v[178:181], v[162:165], v[14:17]
	s_waitcnt lgkmcnt(6)
	v_mfma_f32_16x16x32_bf16 v[50:53], v[214:217], v[198:201], v[50:53]
	s_waitcnt lgkmcnt(5)
	v_mfma_f32_16x16x32_bf16 v[54:57], v[214:217], v[202:205], v[54:57]
	s_waitcnt lgkmcnt(4)
	v_mfma_f32_16x16x32_bf16 v[58:61], v[218:221], v[198:201], v[58:61]
	v_mfma_f32_16x16x32_bf16 v[62:65], v[218:221], v[202:205], v[62:65]
	s_waitcnt lgkmcnt(3)
	v_mfma_f32_16x16x32_bf16 v[18:21], v[214:217], v[206:209], v[18:21]
	v_mfma_f32_16x16x32_bf16 v[26:29], v[218:221], v[206:209], v[26:29]
	s_waitcnt lgkmcnt(2)
	v_mfma_f32_16x16x32_bf16 v[22:25], v[214:217], v[210:213], v[22:25]
	v_mfma_f32_16x16x32_bf16 v[30:33], v[218:221], v[210:213], v[30:33]
	s_waitcnt lgkmcnt(1)
	v_mfma_f32_16x16x32_bf16 v[34:37], v[222:225], v[198:201], v[34:37]
	v_mfma_f32_16x16x32_bf16 v[38:41], v[222:225], v[202:205], v[38:41]
	v_mfma_f32_16x16x32_bf16 v[2:5], v[222:225], v[206:209], v[2:5]
	v_mfma_f32_16x16x32_bf16 v[6:9], v[222:225], v[210:213], v[6:9]
	s_waitcnt lgkmcnt(0)
	v_mfma_f32_16x16x32_bf16 v[42:45], v[226:229], v[198:201], v[42:45]
	v_mfma_f32_16x16x32_bf16 v[46:49], v[226:229], v[202:205], v[46:49]
	v_mfma_f32_16x16x32_bf16 v[10:13], v[226:229], v[206:209], v[10:13]
	v_mfma_f32_16x16x32_bf16 v[14:17], v[226:229], v[210:213], v[14:17]
	s_nop 7
	s_nop 7
	v_permlane16_swap_b32_e32 v50, v54
	v_permlane16_swap_b32_e32 v51, v55
	v_permlane16_swap_b32_e32 v52, v56
	v_permlane16_swap_b32_e32 v53, v57
	v_permlane16_swap_b32_e32 v58, v62
	v_permlane16_swap_b32_e32 v59, v63
	v_permlane16_swap_b32_e32 v60, v64
	v_permlane16_swap_b32_e32 v61, v65
	v_permlane16_swap_b32_e32 v34, v38
	v_permlane16_swap_b32_e32 v35, v39
	v_permlane16_swap_b32_e32 v36, v40
	v_permlane16_swap_b32_e32 v37, v41
	v_permlane16_swap_b32_e32 v42, v46
	v_permlane16_swap_b32_e32 v43, v47
	v_permlane16_swap_b32_e32 v44, v48
	v_permlane16_swap_b32_e32 v45, v49
	v_permlane16_swap_b32_e32 v18, v22
	v_permlane16_swap_b32_e32 v19, v23
	v_permlane16_swap_b32_e32 v20, v24
	v_permlane16_swap_b32_e32 v21, v25
	v_permlane16_swap_b32_e32 v26, v30
	v_permlane16_swap_b32_e32 v27, v31
	v_permlane16_swap_b32_e32 v28, v32
	v_permlane16_swap_b32_e32 v29, v33
	v_permlane16_swap_b32_e32 v2, v6
	v_permlane16_swap_b32_e32 v3, v7
	v_permlane16_swap_b32_e32 v4, v8
	v_permlane16_swap_b32_e32 v5, v9
	v_permlane16_swap_b32_e32 v10, v14
	v_permlane16_swap_b32_e32 v11, v15
	v_permlane16_swap_b32_e32 v12, v16
	v_permlane16_swap_b32_e32 v13, v17
	s_waitcnt lgkmcnt(0)
	s_barrier
	s_branch .LBB0_952
